# v57 + ffn_out K-loops: in each 6-load stage segment the two loads of the HBM-streamed A operand issue before the four weight loads
# baseline (speedup 1.0000x reference)
; #define PG8_STAGE(bufoff, gbase, voff) do { _Pragma("unroll") for (int _i = 0; _i < 2; ++_i) \
;         asm volatile("s_mov_b32 m0, %0\n\ts_nop 0\n\tglobal_load_lds_dwordx4 %1, %2" :: "s"(ldsb + (unsigned)((bufoff) + _i * 8192)), "v"((voff)[_i]), "s"(gbase) : "m0", "memory"); } while (0)
; #define PG8_LDA(dst, b, h) do { _Pragma("unroll") for (int m = 0; m < 4; ++m) _Pragma("unroll") for (int k = 0; k < 2; ++k) dst[m][k] = *(const PG8_LAS bf16x8*)(lds + PG8_SA(b, h) + aoff + m * 2048 + k * 1024); } while (0)
; #define PG8_LDB(dst, b, h) do { _Pragma("unroll") for (int n = 0; n < 2; ++n) _Pragma("unroll") for (int k = 0; k < 2; ++k) dst[n][k] = *(const PG8_LAS bf16x8*)(lds + PG8_SB(b, h) + boff + n * 2048 + k * 1024); } while (0)
; #define PG8_MMA(ai, bj, At, Bt) do { __builtin_amdgcn_s_setprio(1); _Pragma("unroll") for (int m = 0; m < 4; ++m) _Pragma("unroll") for (int n = 0; n < 2; ++n) _Pragma("unroll") for (int k = 0; k < 2; ++k) \
;         acc[ai][bj][m][n] = __builtin_amdgcn_mfma_f32_16x16x32_bf16(Bt[n][k], At[m][k], acc[ai][bj][m][n], 0, 0, 0); __builtin_amdgcn_s_setprio(0); } while (0)
; #define PG8_WAIT_V(n) asm volatile("s_waitcnt vmcnt(" #n ")" ::: "memory")
; #define PG8_WAIT_L(n) asm volatile("s_waitcnt lgkmcnt(" #n ")" ::: "memory")
; #define PG8_BAR __builtin_amdgcn_s_barrier()
; #define PG8_SCHED __builtin_amdgcn_sched_barrier(0)
; template <class Epi, class Sched, bool ALIGN_EPI = false, bool SP2 = false>
; __device__ __forceinline__ void gemm_phase(PG8_LAS unsigned char* lds, const Gemm g, const Sched& S, const Epi& E, const int wv) {
;     ...
;             PG8_LDB(B0, 0, 0); PG8_LDB(B1, 0, 1); PG8_SCHED; PG8_LDA(At, 0, 0); PG8_STAGE(PG8_SA(1, 1), a1 + hstepA, voffA);
;             PG8_WAIT_V(8); PG8_WAIT_L(0); PG8_BAR; PG8_MMA(0, 0, At, B0); PG8_MMA(0, 1, At, B1); PG8_BAR; PG8_SCHED;
;             PG8_LDA(At, 0, 1); PG8_STAGE(PG8_SB(0, 0), b2, voffB); PG8_STAGE(PG8_SB(0, 1), b2 + hstepB, voffB); PG8_STAGE(PG8_SA(0, 0), a2, voffA);
;             PG8_WAIT_V(8); PG8_WAIT_L(0); PG8_BAR; PG8_MMA(1, 0, At, B0); PG8_MMA(1, 1, At, B1); PG8_BAR; PG8_SCHED;
.LBB0_343:
	v_add_u32_e32 v140, 0x10000, v220
	v_add_u32_e32 v159, 0x14000, v220
	ds_read_b128 v[128:131], v140
	ds_read_b128 v[132:135], v140 offset:1024
	ds_read_b128 v[136:139], v140 offset:2048
	ds_read_b128 v[140:143], v140 offset:3072
	ds_read_b128 v[144:147], v159
	ds_read_b128 v[148:151], v159 offset:1024
	ds_read_b128 v[152:155], v159 offset:2048
	ds_read_b128 v[160:163], v159 offset:3072
	s_add_i32 s62, s30, 2
	s_cmp_eq_u32 s23, s30
	s_cselect_b32 s36, s24, s85
	s_cselect_b32 s37, s25, vcc_lo
	s_cselect_b32 s34, s26, vcc_hi
	s_cselect_b32 s35, s27, s79
	s_add_u32 s30, s36, 0x80
	s_addc_u32 s31, s37, 0
	ds_read_b128 v[164:167], v221
	ds_read_b128 v[168:171], v221 offset:1024
	ds_read_b128 v[172:175], v221 offset:2048
	ds_read_b128 v[176:179], v221 offset:3072
	ds_read_b128 v[180:183], v221 offset:4096
	ds_read_b128 v[184:187], v221 offset:5120
	ds_read_b128 v[188:191], v221 offset:6144
	ds_read_b128 v[194:197], v221 offset:7168
	s_mov_b32 m0, s93
	s_nop 0
	global_load_lds_dwordx4 v208, s[28:29]
	s_nop 0
	s_mov_b32 m0, s58
	s_nop 0
	global_load_lds_dwordx4 v210, s[28:29]
	s_waitcnt vmcnt(8) lgkmcnt(0)
	s_setprio 1
	s_barrier
	v_mfma_f32_16x16x32_bf16 v[124:127], v[128:131], v[164:167], v[124:127]
	v_mfma_f32_16x16x32_bf16 v[120:123], v[136:139], v[164:167], v[120:123]
	v_mfma_f32_16x16x32_bf16 v[108:111], v[128:131], v[172:175], v[108:111]
	v_mfma_f32_16x16x32_bf16 v[104:107], v[136:139], v[172:175], v[104:107]
	v_mfma_f32_16x16x32_bf16 v[92:95], v[128:131], v[180:183], v[92:95]
	v_mfma_f32_16x16x32_bf16 v[88:91], v[136:139], v[180:183], v[88:91]
	v_mfma_f32_16x16x32_bf16 v[76:79], v[128:131], v[188:191], v[76:79]
	v_mfma_f32_16x16x32_bf16 v[72:75], v[136:139], v[188:191], v[72:75]
	v_mfma_f32_16x16x32_bf16 v[124:127], v[132:135], v[168:171], v[124:127]
	v_mfma_f32_16x16x32_bf16 v[120:123], v[140:143], v[168:171], v[120:123]
	v_mfma_f32_16x16x32_bf16 v[108:111], v[132:135], v[176:179], v[108:111]
	v_mfma_f32_16x16x32_bf16 v[104:107], v[140:143], v[176:179], v[104:107]
	v_mfma_f32_16x16x32_bf16 v[92:95], v[132:135], v[184:187], v[92:95]
	v_mfma_f32_16x16x32_bf16 v[88:91], v[140:143], v[184:187], v[88:91]
	v_mfma_f32_16x16x32_bf16 v[76:79], v[132:135], v[194:197], v[76:79]
	v_mfma_f32_16x16x32_bf16 v[72:75], v[140:143], v[194:197], v[72:75]
	v_mfma_f32_16x16x32_bf16 v[116:119], v[144:147], v[164:167], v[116:119]
	v_mfma_f32_16x16x32_bf16 v[112:115], v[152:155], v[164:167], v[112:115]
	v_mfma_f32_16x16x32_bf16 v[100:103], v[144:147], v[172:175], v[100:103]
	v_mfma_f32_16x16x32_bf16 v[96:99], v[152:155], v[172:175], v[96:99]
	v_mfma_f32_16x16x32_bf16 v[84:87], v[144:147], v[180:183], v[84:87]
	v_mfma_f32_16x16x32_bf16 v[80:83], v[152:155], v[180:183], v[80:83]
	v_mfma_f32_16x16x32_bf16 v[68:71], v[144:147], v[188:191], v[68:71]
	v_mfma_f32_16x16x32_bf16 v[64:67], v[152:155], v[188:191], v[64:67]
	v_mfma_f32_16x16x32_bf16 v[116:119], v[148:151], v[168:171], v[116:119]
	v_mfma_f32_16x16x32_bf16 v[112:115], v[160:163], v[168:171], v[112:115]
	v_mfma_f32_16x16x32_bf16 v[100:103], v[148:151], v[176:179], v[100:103]
	v_mfma_f32_16x16x32_bf16 v[96:99], v[160:163], v[176:179], v[96:99]
	v_mfma_f32_16x16x32_bf16 v[84:87], v[148:151], v[184:187], v[84:87]
	v_mfma_f32_16x16x32_bf16 v[80:83], v[160:163], v[184:187], v[80:83]
	v_mfma_f32_16x16x32_bf16 v[68:71], v[148:151], v[194:197], v[68:71]
	v_mfma_f32_16x16x32_bf16 v[64:67], v[160:163], v[194:197], v[64:67]
	s_setprio 0
	s_barrier
	ds_read_b128 v[164:167], v221 offset:16384
	ds_read_b128 v[168:171], v221 offset:17408
	ds_read_b128 v[172:175], v221 offset:18432
	ds_read_b128 v[176:179], v221 offset:19456
	ds_read_b128 v[180:183], v221 offset:20480
	ds_read_b128 v[184:187], v221 offset:21504
	ds_read_b128 v[188:191], v221 offset:22528
	ds_read_b128 v[194:197], v221 offset:23552
	s_mov_b32 m0, s46
	s_nop 0
	global_load_lds_dwordx4 v208, s[36:37]
	s_mov_b32 m0, s51
	s_nop 0
	global_load_lds_dwordx4 v210, s[36:37]
	s_mov_b32 m0, s47
	s_nop 0
	global_load_lds_dwordx4 v209, s[34:35]
	s_add_u32 s8, s34, 0x160000
	s_mov_b32 m0, s48
	s_nop 0
	global_load_lds_dwordx4 v211, s[34:35]
	s_addc_u32 s9, s35, 0
	s_mov_b32 m0, s49
	s_nop 0
	global_load_lds_dwordx4 v209, s[8:9]
	s_nop 0
	s_mov_b32 m0, s50
	s_nop 0
	global_load_lds_dwordx4 v211, s[8:9]
	s_nop 0
	s_nop 0
	s_waitcnt vmcnt(8) lgkmcnt(0)
	s_setprio 1
	s_barrier
	v_mfma_f32_16x16x32_bf16 v[60:63], v[128:131], v[164:167], v[60:63]
	v_mfma_f32_16x16x32_bf16 v[56:59], v[136:139], v[164:167], v[56:59]
	v_mfma_f32_16x16x32_bf16 v[44:47], v[128:131], v[172:175], v[44:47]
	v_mfma_f32_16x16x32_bf16 v[40:43], v[136:139], v[172:175], v[40:43]
	v_mfma_f32_16x16x32_bf16 v[28:31], v[128:131], v[180:183], v[28:31]
	v_mfma_f32_16x16x32_bf16 v[24:27], v[136:139], v[180:183], v[24:27]
	v_mfma_f32_16x16x32_bf16 v[12:15], v[128:131], v[188:191], v[12:15]
	v_mfma_f32_16x16x32_bf16 v[8:11], v[136:139], v[188:191], v[8:11]
	v_mfma_f32_16x16x32_bf16 v[60:63], v[132:135], v[168:171], v[60:63]
	v_mfma_f32_16x16x32_bf16 v[56:59], v[140:143], v[168:171], v[56:59]
	v_mfma_f32_16x16x32_bf16 v[44:47], v[132:135], v[176:179], v[44:47]
	v_mfma_f32_16x16x32_bf16 v[40:43], v[140:143], v[176:179], v[40:43]
	v_mfma_f32_16x16x32_bf16 v[28:31], v[132:135], v[184:187], v[28:31]
	v_mfma_f32_16x16x32_bf16 v[24:27], v[140:143], v[184:187], v[24:27]
	v_mfma_f32_16x16x32_bf16 v[12:15], v[132:135], v[194:197], v[12:15]
	v_mfma_f32_16x16x32_bf16 v[8:11], v[140:143], v[194:197], v[8:11]
	v_mfma_f32_16x16x32_bf16 v[52:55], v[144:147], v[164:167], v[52:55]
	v_mfma_f32_16x16x32_bf16 v[48:51], v[152:155], v[164:167], v[48:51]
	v_mfma_f32_16x16x32_bf16 v[36:39], v[144:147], v[172:175], v[36:39]
	v_mfma_f32_16x16x32_bf16 v[32:35], v[152:155], v[172:175], v[32:35]
	v_mfma_f32_16x16x32_bf16 v[20:23], v[144:147], v[180:183], v[20:23]
	v_mfma_f32_16x16x32_bf16 v[16:19], v[152:155], v[180:183], v[16:19]
	v_mfma_f32_16x16x32_bf16 v[4:7], v[144:147], v[188:191], v[4:7]
	v_mfma_f32_16x16x32_bf16 v[0:3], v[152:155], v[188:191], v[0:3]
	v_mfma_f32_16x16x32_bf16 v[52:55], v[148:151], v[168:171], v[52:55]
	v_mfma_f32_16x16x32_bf16 v[48:51], v[160:163], v[168:171], v[48:51]
	v_mfma_f32_16x16x32_bf16 v[36:39], v[148:151], v[176:179], v[36:39]
	v_mfma_f32_16x16x32_bf16 v[32:35], v[160:163], v[176:179], v[32:35]
	v_mfma_f32_16x16x32_bf16 v[20:23], v[148:151], v[184:187], v[20:23]
	v_mfma_f32_16x16x32_bf16 v[16:19], v[160:163], v[184:187], v[16:19]
	v_mfma_f32_16x16x32_bf16 v[4:7], v[148:151], v[194:197], v[4:7]
	v_mfma_f32_16x16x32_bf16 v[0:3], v[160:163], v[194:197], v[0:3]
	s_setprio 0
	s_barrier
; #define PG8_STAGE(bufoff, gbase, voff) do { _Pragma("unroll") for (int _i = 0; _i < 2; ++_i) \
;         asm volatile("s_mov_b32 m0, %0\n\ts_nop 0\n\tglobal_load_lds_dwordx4 %1, %2" :: "s"(ldsb + (unsigned)((bufoff) + _i * 8192)), "v"((voff)[_i]), "s"(gbase) : "m0", "memory"); } while (0)
; #define PG8_LDA(dst, b, h) do { _Pragma("unroll") for (int m = 0; m < 4; ++m) _Pragma("unroll") for (int k = 0; k < 2; ++k) dst[m][k] = *(const PG8_LAS bf16x8*)(lds + PG8_SA(b, h) + aoff + m * 2048 + k * 1024); } while (0)
; #define PG8_LDB(dst, b, h) do { _Pragma("unroll") for (int n = 0; n < 2; ++n) _Pragma("unroll") for (int k = 0; k < 2; ++k) dst[n][k] = *(const PG8_LAS bf16x8*)(lds + PG8_SB(b, h) + boff + n * 2048 + k * 1024); } while (0)
; #define PG8_MMA(ai, bj, At, Bt) do { __builtin_amdgcn_s_setprio(1); _Pragma("unroll") for (int m = 0; m < 4; ++m) _Pragma("unroll") for (int n = 0; n < 2; ++n) _Pragma("unroll") for (int k = 0; k < 2; ++k) \
;         acc[ai][bj][m][n] = __builtin_amdgcn_mfma_f32_16x16x32_bf16(Bt[n][k], At[m][k], acc[ai][bj][m][n], 0, 0, 0); __builtin_amdgcn_s_setprio(0); } while (0)
; #define PG8_WAIT_V(n) asm volatile("s_waitcnt vmcnt(" #n ")" ::: "memory")
; #define PG8_WAIT_L(n) asm volatile("s_waitcnt lgkmcnt(" #n ")" ::: "memory")
; #define PG8_BAR __builtin_amdgcn_s_barrier()
; #define PG8_SCHED __builtin_amdgcn_sched_barrier(0)
; template <class Epi, class Sched, bool ALIGN_EPI = false, bool SP2 = false>
; __device__ __forceinline__ void gemm_phase(PG8_LAS unsigned char* lds, const Gemm g, const Sched& S, const Epi& E, const int wv) {
;     ...
;             PG8_LDB(B0, 1, 0); PG8_LDB(B1, 1, 1); PG8_SCHED; PG8_LDA(At, 1, 0); PG8_STAGE(PG8_SA(0, 1), a2 + hstepA, voffA);
;             PG8_WAIT_V(8); PG8_WAIT_L(0); PG8_BAR; PG8_MMA(0, 0, At, B0); PG8_MMA(0, 1, At, B1); PG8_BAR; PG8_SCHED;
;             PG8_LDA(At, 1, 1); PG8_STAGE(PG8_SB(1, 0), b3, voffB); PG8_STAGE(PG8_SB(1, 1), b3 + hstepB, voffB); PG8_STAGE(PG8_SA(1, 0), a3, voffA);
;             PG8_WAIT_V(8); PG8_WAIT_L(0); PG8_BAR; PG8_MMA(1, 0, At, B0); PG8_MMA(1, 1, At, B1); PG8_BAR; PG8_SCHED;
	v_add_u32_e32 v140, 0x18000, v220
	v_add_u32_e32 v159, 0x1c000, v220
	ds_read_b128 v[128:131], v140
	ds_read_b128 v[132:135], v140 offset:1024
	ds_read_b128 v[136:139], v140 offset:2048
	ds_read_b128 v[140:143], v140 offset:3072
	ds_read_b128 v[144:147], v159
	ds_read_b128 v[148:151], v159 offset:1024
	ds_read_b128 v[152:155], v159 offset:2048
	ds_read_b128 v[160:163], v159 offset:3072
	ds_read_b128 v[164:167], v221 offset:32768
	ds_read_b128 v[168:171], v221 offset:33792
	ds_read_b128 v[172:175], v221 offset:34816
	ds_read_b128 v[176:179], v221 offset:35840
	ds_read_b128 v[180:183], v221 offset:36864
	ds_read_b128 v[184:187], v221 offset:37888
	ds_read_b128 v[188:191], v221 offset:38912
	ds_read_b128 v[194:197], v221 offset:39936
	s_add_u32 s8, s36, 0x160000
	s_addc_u32 s9, s37, 0
	s_mov_b32 m0, s52
	s_nop 0
	global_load_lds_dwordx4 v208, s[8:9]
	s_nop 0
	s_mov_b32 m0, s53
	s_nop 0
	global_load_lds_dwordx4 v210, s[8:9]
	s_waitcnt vmcnt(8) lgkmcnt(0)
	s_setprio 1
	s_barrier
	v_mfma_f32_16x16x32_bf16 v[124:127], v[128:131], v[164:167], v[124:127]
	v_mfma_f32_16x16x32_bf16 v[120:123], v[136:139], v[164:167], v[120:123]
	v_mfma_f32_16x16x32_bf16 v[108:111], v[128:131], v[172:175], v[108:111]
	v_mfma_f32_16x16x32_bf16 v[104:107], v[136:139], v[172:175], v[104:107]
	v_mfma_f32_16x16x32_bf16 v[92:95], v[128:131], v[180:183], v[92:95]
	v_mfma_f32_16x16x32_bf16 v[88:91], v[136:139], v[180:183], v[88:91]
	v_mfma_f32_16x16x32_bf16 v[76:79], v[128:131], v[188:191], v[76:79]
	v_mfma_f32_16x16x32_bf16 v[72:75], v[136:139], v[188:191], v[72:75]
	v_mfma_f32_16x16x32_bf16 v[124:127], v[132:135], v[168:171], v[124:127]
	v_mfma_f32_16x16x32_bf16 v[120:123], v[140:143], v[168:171], v[120:123]
	v_mfma_f32_16x16x32_bf16 v[108:111], v[132:135], v[176:179], v[108:111]
	v_mfma_f32_16x16x32_bf16 v[104:107], v[140:143], v[176:179], v[104:107]
	v_mfma_f32_16x16x32_bf16 v[92:95], v[132:135], v[184:187], v[92:95]
	v_mfma_f32_16x16x32_bf16 v[88:91], v[140:143], v[184:187], v[88:91]
	v_mfma_f32_16x16x32_bf16 v[76:79], v[132:135], v[194:197], v[76:79]
	v_mfma_f32_16x16x32_bf16 v[72:75], v[140:143], v[194:197], v[72:75]
	v_mfma_f32_16x16x32_bf16 v[116:119], v[144:147], v[164:167], v[116:119]
	v_mfma_f32_16x16x32_bf16 v[112:115], v[152:155], v[164:167], v[112:115]
	v_mfma_f32_16x16x32_bf16 v[100:103], v[144:147], v[172:175], v[100:103]
	v_mfma_f32_16x16x32_bf16 v[96:99], v[152:155], v[172:175], v[96:99]
	v_mfma_f32_16x16x32_bf16 v[84:87], v[144:147], v[180:183], v[84:87]
	v_mfma_f32_16x16x32_bf16 v[80:83], v[152:155], v[180:183], v[80:83]
	v_mfma_f32_16x16x32_bf16 v[68:71], v[144:147], v[188:191], v[68:71]
	v_mfma_f32_16x16x32_bf16 v[64:67], v[152:155], v[188:191], v[64:67]
	v_mfma_f32_16x16x32_bf16 v[116:119], v[148:151], v[168:171], v[116:119]
	v_mfma_f32_16x16x32_bf16 v[112:115], v[160:163], v[168:171], v[112:115]
	v_mfma_f32_16x16x32_bf16 v[100:103], v[148:151], v[176:179], v[100:103]
	v_mfma_f32_16x16x32_bf16 v[96:99], v[160:163], v[176:179], v[96:99]
	v_mfma_f32_16x16x32_bf16 v[84:87], v[148:151], v[184:187], v[84:87]
	v_mfma_f32_16x16x32_bf16 v[80:83], v[160:163], v[184:187], v[80:83]
	v_mfma_f32_16x16x32_bf16 v[68:71], v[148:151], v[194:197], v[68:71]
	v_mfma_f32_16x16x32_bf16 v[64:67], v[160:163], v[194:197], v[64:67]
	s_setprio 0
	s_barrier
	ds_read_b128 v[164:167], v221 offset:49152
	ds_read_b128 v[168:171], v221 offset:50176
	ds_read_b128 v[172:175], v221 offset:51200
	ds_read_b128 v[176:179], v221 offset:52224
	ds_read_b128 v[180:183], v221 offset:53248
	ds_read_b128 v[184:187], v221 offset:54272
	ds_read_b128 v[188:191], v221 offset:55296
	ds_read_b128 v[194:197], v221 offset:56320
	s_add_u32 s8, s34, 0x80
	s_addc_u32 s9, s35, 0
	s_mov_b32 m0, s83
	s_nop 0
	global_load_lds_dwordx4 v208, s[30:31]
	s_mov_b32 m0, s60
	s_nop 0
	global_load_lds_dwordx4 v210, s[30:31]
	s_mov_b32 m0, s86
	s_nop 0
	global_load_lds_dwordx4 v209, s[8:9]
	s_nop 0
	s_mov_b32 m0, s87
	s_nop 0
	global_load_lds_dwordx4 v211, s[8:9]
	s_add_u32 s8, s34, 0x160080
	s_addc_u32 s9, s35, 0
	s_mov_b32 m0, s89
	s_nop 0
	global_load_lds_dwordx4 v209, s[8:9]
	s_nop 0
	s_mov_b32 m0, s92
	s_nop 0
	global_load_lds_dwordx4 v211, s[8:9]
	s_nop 0
	s_nop 0
	s_waitcnt vmcnt(8) lgkmcnt(0)
	s_setprio 1
	s_barrier
	v_mfma_f32_16x16x32_bf16 v[60:63], v[128:131], v[164:167], v[60:63]
	v_mfma_f32_16x16x32_bf16 v[56:59], v[136:139], v[164:167], v[56:59]
	v_mfma_f32_16x16x32_bf16 v[44:47], v[128:131], v[172:175], v[44:47]
	v_mfma_f32_16x16x32_bf16 v[40:43], v[136:139], v[172:175], v[40:43]
	v_mfma_f32_16x16x32_bf16 v[28:31], v[128:131], v[180:183], v[28:31]
	v_mfma_f32_16x16x32_bf16 v[24:27], v[136:139], v[180:183], v[24:27]
	v_mfma_f32_16x16x32_bf16 v[12:15], v[128:131], v[188:191], v[12:15]
	v_mfma_f32_16x16x32_bf16 v[8:11], v[136:139], v[188:191], v[8:11]
	v_mfma_f32_16x16x32_bf16 v[60:63], v[132:135], v[168:171], v[60:63]
	v_mfma_f32_16x16x32_bf16 v[56:59], v[140:143], v[168:171], v[56:59]
	v_mfma_f32_16x16x32_bf16 v[44:47], v[132:135], v[176:179], v[44:47]
	v_mfma_f32_16x16x32_bf16 v[40:43], v[140:143], v[176:179], v[40:43]
	v_mfma_f32_16x16x32_bf16 v[28:31], v[132:135], v[184:187], v[28:31]
	v_mfma_f32_16x16x32_bf16 v[24:27], v[140:143], v[184:187], v[24:27]
	v_mfma_f32_16x16x32_bf16 v[12:15], v[132:135], v[194:197], v[12:15]
	v_mfma_f32_16x16x32_bf16 v[8:11], v[140:143], v[194:197], v[8:11]
	v_mfma_f32_16x16x32_bf16 v[52:55], v[144:147], v[164:167], v[52:55]
	v_mfma_f32_16x16x32_bf16 v[48:51], v[152:155], v[164:167], v[48:51]
	v_mfma_f32_16x16x32_bf16 v[36:39], v[144:147], v[172:175], v[36:39]
	v_mfma_f32_16x16x32_bf16 v[32:35], v[152:155], v[172:175], v[32:35]
	v_mfma_f32_16x16x32_bf16 v[20:23], v[144:147], v[180:183], v[20:23]
	v_mfma_f32_16x16x32_bf16 v[16:19], v[152:155], v[180:183], v[16:19]
	v_mfma_f32_16x16x32_bf16 v[4:7], v[144:147], v[188:191], v[4:7]
	v_mfma_f32_16x16x32_bf16 v[0:3], v[152:155], v[188:191], v[0:3]
	v_mfma_f32_16x16x32_bf16 v[52:55], v[148:151], v[168:171], v[52:55]
	v_mfma_f32_16x16x32_bf16 v[48:51], v[160:163], v[168:171], v[48:51]
	v_mfma_f32_16x16x32_bf16 v[36:39], v[148:151], v[176:179], v[36:39]
	v_mfma_f32_16x16x32_bf16 v[32:35], v[160:163], v[176:179], v[32:35]
	v_mfma_f32_16x16x32_bf16 v[20:23], v[148:151], v[184:187], v[20:23]
	v_mfma_f32_16x16x32_bf16 v[16:19], v[160:163], v[184:187], v[16:19]
	v_mfma_f32_16x16x32_bf16 v[4:7], v[148:151], v[194:197], v[4:7]
	v_mfma_f32_16x16x32_bf16 v[0:3], v[160:163], v[194:197], v[0:3]
	s_setprio 0
	s_barrier
	s_add_u32 s85, s85, 0x100
	s_addc_u32 vcc_lo, vcc_lo, 0
	s_add_u32 vcc_hi, vcc_hi, 0x100
	s_addc_u32 s79, s79, 0
	s_add_u32 s28, s28, 0x100
	s_addc_u32 s29, s29, 0
	s_cmp_ge_i32 s62, s40
	s_mov_b32 s30, s62
	s_cbranch_scc0 .LBB0_343
	s_mov_b32 s79, 0xc00000
	s_and_b64 vcc, exec, s[18:19]
	s_cbranch_vccz .LBB0_346

; #define PG8_STAGE(bufoff, gbase, voff) do { _Pragma("unroll") for (int _i = 0; _i < 2; ++_i) \
;         asm volatile("s_mov_b32 m0, %0\n\ts_nop 0\n\tglobal_load_lds_dwordx4 %1, %2" :: "s"(ldsb + (unsigned)((bufoff) + _i * 8192)), "v"((voff)[_i]), "s"(gbase) : "m0", "memory"); } while (0)
; #define PG8_LDA(dst, b, h) do { _Pragma("unroll") for (int m = 0; m < 4; ++m) _Pragma("unroll") for (int k = 0; k < 2; ++k) dst[m][k] = *(const PG8_LAS bf16x8*)(lds + PG8_SA(b, h) + aoff + m * 2048 + k * 1024); } while (0)
; #define PG8_LDB(dst, b, h) do { _Pragma("unroll") for (int n = 0; n < 2; ++n) _Pragma("unroll") for (int k = 0; k < 2; ++k) dst[n][k] = *(const PG8_LAS bf16x8*)(lds + PG8_SB(b, h) + boff + n * 2048 + k * 1024); } while (0)
; #define PG8_MMA(ai, bj, At, Bt) do { __builtin_amdgcn_s_setprio(1); _Pragma("unroll") for (int m = 0; m < 4; ++m) _Pragma("unroll") for (int n = 0; n < 2; ++n) _Pragma("unroll") for (int k = 0; k < 2; ++k) \
;         acc[ai][bj][m][n] = __builtin_amdgcn_mfma_f32_16x16x32_bf16(Bt[n][k], At[m][k], acc[ai][bj][m][n], 0, 0, 0); __builtin_amdgcn_s_setprio(0); } while (0)
; #define PG8_WAIT_V(n) asm volatile("s_waitcnt vmcnt(" #n ")" ::: "memory")
; #define PG8_WAIT_L(n) asm volatile("s_waitcnt lgkmcnt(" #n ")" ::: "memory")
; #define PG8_BAR __builtin_amdgcn_s_barrier()
; #define PG8_SCHED __builtin_amdgcn_sched_barrier(0)
; template <class Epi, class Sched, bool ALIGN_EPI = false, bool SP2 = false>
; __device__ __forceinline__ void gemm_phase(PG8_LAS unsigned char* lds, const Gemm g, const Sched& S, const Epi& E, const int wv) {
;     ...
;             PG8_LDB(B0, 0, 0); PG8_LDB(B1, 0, 1); PG8_SCHED; PG8_LDA(At, 0, 0); PG8_STAGE(PG8_SA(1, 1), a1 + hstepA, voffA);
;             PG8_WAIT_V(8); PG8_WAIT_L(0); PG8_BAR; PG8_MMA(0, 0, At, B0); PG8_MMA(0, 1, At, B1); PG8_BAR; PG8_SCHED;
;             PG8_LDA(At, 0, 1); PG8_STAGE(PG8_SB(0, 0), b2, voffB); PG8_STAGE(PG8_SB(0, 1), b2 + hstepB, voffB); PG8_STAGE(PG8_SA(0, 0), a2, voffA);
;             PG8_WAIT_V(8); PG8_WAIT_L(0); PG8_BAR; PG8_MMA(1, 0, At, B0); PG8_MMA(1, 1, At, B1); PG8_BAR; PG8_SCHED;
.LBB0_396:
	v_add_u32_e32 v140, 0x10000, v240
	v_add_u32_e32 v156, 0x14000, v240
	ds_read_b128 v[128:131], v140
	ds_read_b128 v[132:135], v140 offset:1024
	ds_read_b128 v[136:139], v140 offset:2048
	ds_read_b128 v[140:143], v140 offset:3072
	ds_read_b128 v[144:147], v156
	ds_read_b128 v[148:151], v156 offset:1024
	ds_read_b128 v[152:155], v156 offset:2048
	ds_read_b128 v[156:159], v156 offset:3072
	s_add_i32 vcc_hi, s30, 2
	s_cmp_eq_u32 s25, s30
	s_cselect_b32 s36, s26, s62
	s_cselect_b32 s37, s27, s79
	s_cselect_b32 s34, s28, s97
	s_cselect_b32 s35, s29, vcc_lo
	s_add_u32 s30, s36, 0x80
	s_addc_u32 s31, s37, 0
	ds_read_b128 v[160:163], v194
	ds_read_b128 v[164:167], v194 offset:1024
	ds_read_b128 v[168:171], v194 offset:2048
	ds_read_b128 v[172:175], v194 offset:3072
	ds_read_b128 v[176:179], v194 offset:4096
	ds_read_b128 v[180:183], v194 offset:5120
	ds_read_b128 v[184:187], v194 offset:6144
	ds_read_b128 v[188:191], v194 offset:7168
	s_add_u32 s10, s62, 0x15ff80
	s_addc_u32 s11, s79, 0
	s_mov_b32 m0, s83
	s_nop 0
	global_load_lds_dwordx4 v244, s[10:11]
	s_nop 0
	s_mov_b32 m0, s86
	s_nop 0
	global_load_lds_dwordx4 v246, s[10:11]
	s_waitcnt vmcnt(8) lgkmcnt(0)
	s_setprio 1
	s_barrier
	v_mfma_f32_16x16x32_bf16 v[124:127], v[128:131], v[160:163], v[124:127]
	v_mfma_f32_16x16x32_bf16 v[120:123], v[136:139], v[160:163], v[120:123]
	v_mfma_f32_16x16x32_bf16 v[108:111], v[128:131], v[168:171], v[108:111]
	v_mfma_f32_16x16x32_bf16 v[104:107], v[136:139], v[168:171], v[104:107]
	v_mfma_f32_16x16x32_bf16 v[92:95], v[128:131], v[176:179], v[92:95]
	v_mfma_f32_16x16x32_bf16 v[88:91], v[136:139], v[176:179], v[88:91]
	v_mfma_f32_16x16x32_bf16 v[76:79], v[128:131], v[184:187], v[76:79]
	v_mfma_f32_16x16x32_bf16 v[72:75], v[136:139], v[184:187], v[72:75]
	v_mfma_f32_16x16x32_bf16 v[124:127], v[132:135], v[164:167], v[124:127]
	v_mfma_f32_16x16x32_bf16 v[120:123], v[140:143], v[164:167], v[120:123]
	v_mfma_f32_16x16x32_bf16 v[108:111], v[132:135], v[172:175], v[108:111]
	v_mfma_f32_16x16x32_bf16 v[104:107], v[140:143], v[172:175], v[104:107]
	v_mfma_f32_16x16x32_bf16 v[92:95], v[132:135], v[180:183], v[92:95]
	v_mfma_f32_16x16x32_bf16 v[88:91], v[140:143], v[180:183], v[88:91]
	v_mfma_f32_16x16x32_bf16 v[76:79], v[132:135], v[188:191], v[76:79]
	v_mfma_f32_16x16x32_bf16 v[72:75], v[140:143], v[188:191], v[72:75]
	v_mfma_f32_16x16x32_bf16 v[116:119], v[144:147], v[160:163], v[116:119]
	v_mfma_f32_16x16x32_bf16 v[112:115], v[152:155], v[160:163], v[112:115]
	v_mfma_f32_16x16x32_bf16 v[100:103], v[144:147], v[168:171], v[100:103]
	v_mfma_f32_16x16x32_bf16 v[96:99], v[152:155], v[168:171], v[96:99]
	v_mfma_f32_16x16x32_bf16 v[84:87], v[144:147], v[176:179], v[84:87]
	v_mfma_f32_16x16x32_bf16 v[80:83], v[152:155], v[176:179], v[80:83]
	v_mfma_f32_16x16x32_bf16 v[68:71], v[144:147], v[184:187], v[68:71]
	v_mfma_f32_16x16x32_bf16 v[64:67], v[152:155], v[184:187], v[64:67]
	v_mfma_f32_16x16x32_bf16 v[116:119], v[148:151], v[164:167], v[116:119]
	v_mfma_f32_16x16x32_bf16 v[112:115], v[156:159], v[164:167], v[112:115]
	v_mfma_f32_16x16x32_bf16 v[100:103], v[148:151], v[172:175], v[100:103]
	v_mfma_f32_16x16x32_bf16 v[96:99], v[156:159], v[172:175], v[96:99]
	v_mfma_f32_16x16x32_bf16 v[84:87], v[148:151], v[180:183], v[84:87]
	v_mfma_f32_16x16x32_bf16 v[80:83], v[156:159], v[180:183], v[80:83]
	v_mfma_f32_16x16x32_bf16 v[68:71], v[148:151], v[188:191], v[68:71]
	v_mfma_f32_16x16x32_bf16 v[64:67], v[156:159], v[188:191], v[64:67]
	s_setprio 0
	s_barrier
	ds_read_b128 v[160:163], v194 offset:16384
	ds_read_b128 v[164:167], v194 offset:17408
	ds_read_b128 v[168:171], v194 offset:18432
	ds_read_b128 v[172:175], v194 offset:19456
	ds_read_b128 v[176:179], v194 offset:20480
	ds_read_b128 v[180:183], v194 offset:21504
	ds_read_b128 v[184:187], v194 offset:22528
	ds_read_b128 v[188:191], v194 offset:23552
	s_mov_b32 m0, s33
	s_nop 0
	global_load_lds_dwordx4 v244, s[36:37]
	s_mov_b32 m0, s50
	s_nop 0
	global_load_lds_dwordx4 v246, s[36:37]
	s_mov_b32 m0, s46
	s_nop 0
	global_load_lds_dwordx4 v245, s[34:35]
	s_add_u32 s10, s34, 0x160000
	s_mov_b32 m0, s47
	s_nop 0
	global_load_lds_dwordx4 v247, s[34:35]
	s_addc_u32 s11, s35, 0
	s_mov_b32 m0, s48
	s_nop 0
	global_load_lds_dwordx4 v245, s[10:11]
	s_nop 0
	s_mov_b32 m0, s49
	s_nop 0
	global_load_lds_dwordx4 v247, s[10:11]
	s_nop 0
	s_nop 0
	s_waitcnt vmcnt(8) lgkmcnt(0)
	s_setprio 1
	s_barrier
	v_mfma_f32_16x16x32_bf16 v[60:63], v[128:131], v[160:163], v[60:63]
	v_mfma_f32_16x16x32_bf16 v[56:59], v[136:139], v[160:163], v[56:59]
	v_mfma_f32_16x16x32_bf16 v[44:47], v[128:131], v[168:171], v[44:47]
	v_mfma_f32_16x16x32_bf16 v[40:43], v[136:139], v[168:171], v[40:43]
	v_mfma_f32_16x16x32_bf16 v[28:31], v[128:131], v[176:179], v[28:31]
	v_mfma_f32_16x16x32_bf16 v[24:27], v[136:139], v[176:179], v[24:27]
	v_mfma_f32_16x16x32_bf16 v[12:15], v[128:131], v[184:187], v[12:15]
	v_mfma_f32_16x16x32_bf16 v[8:11], v[136:139], v[184:187], v[8:11]
	v_mfma_f32_16x16x32_bf16 v[60:63], v[132:135], v[164:167], v[60:63]
	v_mfma_f32_16x16x32_bf16 v[56:59], v[140:143], v[164:167], v[56:59]
	v_mfma_f32_16x16x32_bf16 v[44:47], v[132:135], v[172:175], v[44:47]
	v_mfma_f32_16x16x32_bf16 v[40:43], v[140:143], v[172:175], v[40:43]
	v_mfma_f32_16x16x32_bf16 v[28:31], v[132:135], v[180:183], v[28:31]
	v_mfma_f32_16x16x32_bf16 v[24:27], v[140:143], v[180:183], v[24:27]
	v_mfma_f32_16x16x32_bf16 v[12:15], v[132:135], v[188:191], v[12:15]
	v_mfma_f32_16x16x32_bf16 v[8:11], v[140:143], v[188:191], v[8:11]
	v_mfma_f32_16x16x32_bf16 v[52:55], v[144:147], v[160:163], v[52:55]
	v_mfma_f32_16x16x32_bf16 v[48:51], v[152:155], v[160:163], v[48:51]
	v_mfma_f32_16x16x32_bf16 v[36:39], v[144:147], v[168:171], v[36:39]
	v_mfma_f32_16x16x32_bf16 v[32:35], v[152:155], v[168:171], v[32:35]
	v_mfma_f32_16x16x32_bf16 v[20:23], v[144:147], v[176:179], v[20:23]
	v_mfma_f32_16x16x32_bf16 v[16:19], v[152:155], v[176:179], v[16:19]
	v_mfma_f32_16x16x32_bf16 v[4:7], v[144:147], v[184:187], v[4:7]
	v_mfma_f32_16x16x32_bf16 v[0:3], v[152:155], v[184:187], v[0:3]
	v_mfma_f32_16x16x32_bf16 v[52:55], v[148:151], v[164:167], v[52:55]
	v_mfma_f32_16x16x32_bf16 v[48:51], v[156:159], v[164:167], v[48:51]
	v_mfma_f32_16x16x32_bf16 v[36:39], v[148:151], v[172:175], v[36:39]
	v_mfma_f32_16x16x32_bf16 v[32:35], v[156:159], v[172:175], v[32:35]
	v_mfma_f32_16x16x32_bf16 v[20:23], v[148:151], v[180:183], v[20:23]
	v_mfma_f32_16x16x32_bf16 v[16:19], v[156:159], v[180:183], v[16:19]
	v_mfma_f32_16x16x32_bf16 v[4:7], v[148:151], v[188:191], v[4:7]
	v_mfma_f32_16x16x32_bf16 v[0:3], v[156:159], v[188:191], v[0:3]
	s_setprio 0
	s_barrier
; #define PG8_STAGE(bufoff, gbase, voff) do { _Pragma("unroll") for (int _i = 0; _i < 2; ++_i) \
;         asm volatile("s_mov_b32 m0, %0\n\ts_nop 0\n\tglobal_load_lds_dwordx4 %1, %2" :: "s"(ldsb + (unsigned)((bufoff) + _i * 8192)), "v"((voff)[_i]), "s"(gbase) : "m0", "memory"); } while (0)
; #define PG8_LDA(dst, b, h) do { _Pragma("unroll") for (int m = 0; m < 4; ++m) _Pragma("unroll") for (int k = 0; k < 2; ++k) dst[m][k] = *(const PG8_LAS bf16x8*)(lds + PG8_SA(b, h) + aoff + m * 2048 + k * 1024); } while (0)
; #define PG8_LDB(dst, b, h) do { _Pragma("unroll") for (int n = 0; n < 2; ++n) _Pragma("unroll") for (int k = 0; k < 2; ++k) dst[n][k] = *(const PG8_LAS bf16x8*)(lds + PG8_SB(b, h) + boff + n * 2048 + k * 1024); } while (0)
; #define PG8_MMA(ai, bj, At, Bt) do { __builtin_amdgcn_s_setprio(1); _Pragma("unroll") for (int m = 0; m < 4; ++m) _Pragma("unroll") for (int n = 0; n < 2; ++n) _Pragma("unroll") for (int k = 0; k < 2; ++k) \
;         acc[ai][bj][m][n] = __builtin_amdgcn_mfma_f32_16x16x32_bf16(Bt[n][k], At[m][k], acc[ai][bj][m][n], 0, 0, 0); __builtin_amdgcn_s_setprio(0); } while (0)
; #define PG8_WAIT_V(n) asm volatile("s_waitcnt vmcnt(" #n ")" ::: "memory")
; #define PG8_WAIT_L(n) asm volatile("s_waitcnt lgkmcnt(" #n ")" ::: "memory")
; #define PG8_BAR __builtin_amdgcn_s_barrier()
; #define PG8_SCHED __builtin_amdgcn_sched_barrier(0)
; template <class Epi, class Sched, bool ALIGN_EPI = false, bool SP2 = false>
; __device__ __forceinline__ void gemm_phase(PG8_LAS unsigned char* lds, const Gemm g, const Sched& S, const Epi& E, const int wv) {
;     ...
;             PG8_LDB(B0, 1, 0); PG8_LDB(B1, 1, 1); PG8_SCHED; PG8_LDA(At, 1, 0); PG8_STAGE(PG8_SA(0, 1), a2 + hstepA, voffA);
;             PG8_WAIT_V(8); PG8_WAIT_L(0); PG8_BAR; PG8_MMA(0, 0, At, B0); PG8_MMA(0, 1, At, B1); PG8_BAR; PG8_SCHED;
;             PG8_LDA(At, 1, 1); PG8_STAGE(PG8_SB(1, 0), b3, voffB); PG8_STAGE(PG8_SB(1, 1), b3 + hstepB, voffB); PG8_STAGE(PG8_SA(1, 0), a3, voffA);
;             PG8_WAIT_V(8); PG8_WAIT_L(0); PG8_BAR; PG8_MMA(1, 0, At, B0); PG8_MMA(1, 1, At, B1); PG8_BAR; PG8_SCHED;
	v_add_u32_e32 v140, 0x18000, v240
	v_add_u32_e32 v156, 0x1c000, v240
	ds_read_b128 v[128:131], v140
	ds_read_b128 v[132:135], v140 offset:1024
	ds_read_b128 v[136:139], v140 offset:2048
	ds_read_b128 v[140:143], v140 offset:3072
	ds_read_b128 v[144:147], v156
	ds_read_b128 v[148:151], v156 offset:1024
	ds_read_b128 v[152:155], v156 offset:2048
	ds_read_b128 v[156:159], v156 offset:3072
	ds_read_b128 v[160:163], v194 offset:32768
	ds_read_b128 v[164:167], v194 offset:33792
	ds_read_b128 v[168:171], v194 offset:34816
	ds_read_b128 v[172:175], v194 offset:35840
	ds_read_b128 v[176:179], v194 offset:36864
	ds_read_b128 v[180:183], v194 offset:37888
	ds_read_b128 v[184:187], v194 offset:38912
	ds_read_b128 v[188:191], v194 offset:39936
	s_add_u32 s10, s36, 0x160000
	s_addc_u32 s11, s37, 0
	s_mov_b32 m0, s51
	s_nop 0
	global_load_lds_dwordx4 v244, s[10:11]
	s_nop 0
	s_mov_b32 m0, s52
	s_nop 0
	global_load_lds_dwordx4 v246, s[10:11]
	s_waitcnt vmcnt(8) lgkmcnt(0)
	s_setprio 1
	s_barrier
	v_mfma_f32_16x16x32_bf16 v[124:127], v[128:131], v[160:163], v[124:127]
	v_mfma_f32_16x16x32_bf16 v[120:123], v[136:139], v[160:163], v[120:123]
	v_mfma_f32_16x16x32_bf16 v[108:111], v[128:131], v[168:171], v[108:111]
	v_mfma_f32_16x16x32_bf16 v[104:107], v[136:139], v[168:171], v[104:107]
	v_mfma_f32_16x16x32_bf16 v[92:95], v[128:131], v[176:179], v[92:95]
	v_mfma_f32_16x16x32_bf16 v[88:91], v[136:139], v[176:179], v[88:91]
	v_mfma_f32_16x16x32_bf16 v[76:79], v[128:131], v[184:187], v[76:79]
	v_mfma_f32_16x16x32_bf16 v[72:75], v[136:139], v[184:187], v[72:75]
	v_mfma_f32_16x16x32_bf16 v[124:127], v[132:135], v[164:167], v[124:127]
	v_mfma_f32_16x16x32_bf16 v[120:123], v[140:143], v[164:167], v[120:123]
	v_mfma_f32_16x16x32_bf16 v[108:111], v[132:135], v[172:175], v[108:111]
	v_mfma_f32_16x16x32_bf16 v[104:107], v[140:143], v[172:175], v[104:107]
	v_mfma_f32_16x16x32_bf16 v[92:95], v[132:135], v[180:183], v[92:95]
	v_mfma_f32_16x16x32_bf16 v[88:91], v[140:143], v[180:183], v[88:91]
	v_mfma_f32_16x16x32_bf16 v[76:79], v[132:135], v[188:191], v[76:79]
	v_mfma_f32_16x16x32_bf16 v[72:75], v[140:143], v[188:191], v[72:75]
	v_mfma_f32_16x16x32_bf16 v[116:119], v[144:147], v[160:163], v[116:119]
	v_mfma_f32_16x16x32_bf16 v[112:115], v[152:155], v[160:163], v[112:115]
	v_mfma_f32_16x16x32_bf16 v[100:103], v[144:147], v[168:171], v[100:103]
	v_mfma_f32_16x16x32_bf16 v[96:99], v[152:155], v[168:171], v[96:99]
	v_mfma_f32_16x16x32_bf16 v[84:87], v[144:147], v[176:179], v[84:87]
	v_mfma_f32_16x16x32_bf16 v[80:83], v[152:155], v[176:179], v[80:83]
	v_mfma_f32_16x16x32_bf16 v[68:71], v[144:147], v[184:187], v[68:71]
	v_mfma_f32_16x16x32_bf16 v[64:67], v[152:155], v[184:187], v[64:67]
	v_mfma_f32_16x16x32_bf16 v[116:119], v[148:151], v[164:167], v[116:119]
	v_mfma_f32_16x16x32_bf16 v[112:115], v[156:159], v[164:167], v[112:115]
	v_mfma_f32_16x16x32_bf16 v[100:103], v[148:151], v[172:175], v[100:103]
	v_mfma_f32_16x16x32_bf16 v[96:99], v[156:159], v[172:175], v[96:99]
	v_mfma_f32_16x16x32_bf16 v[84:87], v[148:151], v[180:183], v[84:87]
	v_mfma_f32_16x16x32_bf16 v[80:83], v[156:159], v[180:183], v[80:83]
	v_mfma_f32_16x16x32_bf16 v[68:71], v[148:151], v[188:191], v[68:71]
	v_mfma_f32_16x16x32_bf16 v[64:67], v[156:159], v[188:191], v[64:67]
	s_setprio 0
	s_barrier
	ds_read_b128 v[160:163], v194 offset:49152
	ds_read_b128 v[164:167], v194 offset:50176
	ds_read_b128 v[168:171], v194 offset:51200
	ds_read_b128 v[172:175], v194 offset:52224
	ds_read_b128 v[176:179], v194 offset:53248
	ds_read_b128 v[180:183], v194 offset:54272
	ds_read_b128 v[184:187], v194 offset:55296
	ds_read_b128 v[188:191], v194 offset:56320
	s_add_u32 s10, s34, 0x80
	s_addc_u32 s11, s35, 0
	s_mov_b32 m0, s65
	s_nop 0
	global_load_lds_dwordx4 v244, s[30:31]
	s_mov_b32 m0, s71
	s_nop 0
	global_load_lds_dwordx4 v246, s[30:31]
	s_mov_b32 m0, s58
	s_nop 0
	global_load_lds_dwordx4 v245, s[10:11]
	s_nop 0
	s_mov_b32 m0, s60
	s_nop 0
	global_load_lds_dwordx4 v247, s[10:11]
	s_add_u32 s10, s34, 0x160080
	s_addc_u32 s11, s35, 0
	s_mov_b32 m0, s72
	s_nop 0
	global_load_lds_dwordx4 v245, s[10:11]
	s_nop 0
	s_mov_b32 m0, s77
	s_nop 0
	global_load_lds_dwordx4 v247, s[10:11]
	s_nop 0
	s_nop 0
	s_waitcnt vmcnt(8) lgkmcnt(0)
	s_setprio 1
	s_barrier
	v_mfma_f32_16x16x32_bf16 v[60:63], v[128:131], v[160:163], v[60:63]
	v_mfma_f32_16x16x32_bf16 v[56:59], v[136:139], v[160:163], v[56:59]
	v_mfma_f32_16x16x32_bf16 v[44:47], v[128:131], v[168:171], v[44:47]
	v_mfma_f32_16x16x32_bf16 v[40:43], v[136:139], v[168:171], v[40:43]
	v_mfma_f32_16x16x32_bf16 v[28:31], v[128:131], v[176:179], v[28:31]
	v_mfma_f32_16x16x32_bf16 v[24:27], v[136:139], v[176:179], v[24:27]
	v_mfma_f32_16x16x32_bf16 v[12:15], v[128:131], v[184:187], v[12:15]
	v_mfma_f32_16x16x32_bf16 v[8:11], v[136:139], v[184:187], v[8:11]
	v_mfma_f32_16x16x32_bf16 v[60:63], v[132:135], v[164:167], v[60:63]
	v_mfma_f32_16x16x32_bf16 v[56:59], v[140:143], v[164:167], v[56:59]
	v_mfma_f32_16x16x32_bf16 v[44:47], v[132:135], v[172:175], v[44:47]
	v_mfma_f32_16x16x32_bf16 v[40:43], v[140:143], v[172:175], v[40:43]
	v_mfma_f32_16x16x32_bf16 v[28:31], v[132:135], v[180:183], v[28:31]
	v_mfma_f32_16x16x32_bf16 v[24:27], v[140:143], v[180:183], v[24:27]
	v_mfma_f32_16x16x32_bf16 v[12:15], v[132:135], v[188:191], v[12:15]
	v_mfma_f32_16x16x32_bf16 v[8:11], v[140:143], v[188:191], v[8:11]
	v_mfma_f32_16x16x32_bf16 v[52:55], v[144:147], v[160:163], v[52:55]
	v_mfma_f32_16x16x32_bf16 v[48:51], v[152:155], v[160:163], v[48:51]
	v_mfma_f32_16x16x32_bf16 v[36:39], v[144:147], v[168:171], v[36:39]
	v_mfma_f32_16x16x32_bf16 v[32:35], v[152:155], v[168:171], v[32:35]
	v_mfma_f32_16x16x32_bf16 v[20:23], v[144:147], v[176:179], v[20:23]
	v_mfma_f32_16x16x32_bf16 v[16:19], v[152:155], v[176:179], v[16:19]
	v_mfma_f32_16x16x32_bf16 v[4:7], v[144:147], v[184:187], v[4:7]
	v_mfma_f32_16x16x32_bf16 v[0:3], v[152:155], v[184:187], v[0:3]
	v_mfma_f32_16x16x32_bf16 v[52:55], v[148:151], v[164:167], v[52:55]
	v_mfma_f32_16x16x32_bf16 v[48:51], v[156:159], v[164:167], v[48:51]
	v_mfma_f32_16x16x32_bf16 v[36:39], v[148:151], v[172:175], v[36:39]
	v_mfma_f32_16x16x32_bf16 v[32:35], v[156:159], v[172:175], v[32:35]
	v_mfma_f32_16x16x32_bf16 v[20:23], v[148:151], v[180:183], v[20:23]
	v_mfma_f32_16x16x32_bf16 v[16:19], v[156:159], v[180:183], v[16:19]
	v_mfma_f32_16x16x32_bf16 v[4:7], v[148:151], v[188:191], v[4:7]
	v_mfma_f32_16x16x32_bf16 v[0:3], v[156:159], v[188:191], v[0:3]
	s_setprio 0
	s_barrier
	s_add_u32 s62, s62, 0x100
	s_addc_u32 s79, s79, 0
	s_add_u32 s97, s97, 0x100
	s_addc_u32 vcc_lo, vcc_lo, 0
	s_cmp_ge_i32 vcc_hi, s40
	s_mov_b32 s30, vcc_hi
	s_cbranch_scc0 .LBB0_396
	s_mov_b32 s79, 0xc00000
	s_and_b64 vcc, exec, s[20:21]
	s_cbranch_vccz .LBB0_399

; #define PG8_STAGE(bufoff, gbase, voff) do { _Pragma("unroll") for (int _i = 0; _i < 2; ++_i) \
;         asm volatile("s_mov_b32 m0, %0\n\ts_nop 0\n\tglobal_load_lds_dwordx4 %1, %2" :: "s"(ldsb + (unsigned)((bufoff) + _i * 8192)), "v"((voff)[_i]), "s"(gbase) : "m0", "memory"); } while (0)
; #define PG8_LDA(dst, b, h) do { _Pragma("unroll") for (int m = 0; m < 4; ++m) _Pragma("unroll") for (int k = 0; k < 2; ++k) dst[m][k] = *(const PG8_LAS bf16x8*)(lds + PG8_SA(b, h) + aoff + m * 2048 + k * 1024); } while (0)
; #define PG8_LDB(dst, b, h) do { _Pragma("unroll") for (int n = 0; n < 2; ++n) _Pragma("unroll") for (int k = 0; k < 2; ++k) dst[n][k] = *(const PG8_LAS bf16x8*)(lds + PG8_SB(b, h) + boff + n * 2048 + k * 1024); } while (0)
; #define PG8_MMA(ai, bj, At, Bt) do { __builtin_amdgcn_s_setprio(1); _Pragma("unroll") for (int m = 0; m < 4; ++m) _Pragma("unroll") for (int n = 0; n < 2; ++n) _Pragma("unroll") for (int k = 0; k < 2; ++k) \
;         acc[ai][bj][m][n] = __builtin_amdgcn_mfma_f32_16x16x32_bf16(Bt[n][k], At[m][k], acc[ai][bj][m][n], 0, 0, 0); __builtin_amdgcn_s_setprio(0); } while (0)
; #define PG8_WAIT_V(n) asm volatile("s_waitcnt vmcnt(" #n ")" ::: "memory")
; #define PG8_WAIT_L(n) asm volatile("s_waitcnt lgkmcnt(" #n ")" ::: "memory")
; #define PG8_BAR __builtin_amdgcn_s_barrier()
; #define PG8_SCHED __builtin_amdgcn_sched_barrier(0)
; template <class Epi, class Sched, bool ALIGN_EPI = false, bool SP2 = false>
; __device__ __forceinline__ void gemm_phase(PG8_LAS unsigned char* lds, const Gemm g, const Sched& S, const Epi& E, const int wv) {
;     ...
;             PG8_LDB(B0, 0, 0); PG8_LDB(B1, 0, 1); PG8_SCHED; PG8_LDA(At, 0, 0); PG8_STAGE(PG8_SA(1, 1), a1 + hstepA, voffA);
;             PG8_WAIT_V(8); PG8_WAIT_L(0); PG8_BAR; PG8_MMA(0, 0, At, B0); PG8_MMA(0, 1, At, B1); PG8_BAR; PG8_SCHED;
;             PG8_LDA(At, 0, 1); PG8_STAGE(PG8_SB(0, 0), b2, voffB); PG8_STAGE(PG8_SB(0, 1), b2 + hstepB, voffB); PG8_STAGE(PG8_SA(0, 0), a2, voffA);
;             PG8_WAIT_V(8); PG8_WAIT_L(0); PG8_BAR; PG8_MMA(1, 0, At, B0); PG8_MMA(1, 1, At, B1); PG8_BAR; PG8_SCHED;
.LBB0_1244:
	v_add_u32_e32 v140, 0x10000, v196
	v_add_u32_e32 v156, 0x14000, v196
	ds_read_b128 v[128:131], v140
	ds_read_b128 v[132:135], v140 offset:1024
	ds_read_b128 v[136:139], v140 offset:2048
	ds_read_b128 v[140:143], v140 offset:3072
	ds_read_b128 v[144:147], v156
	ds_read_b128 v[148:151], v156 offset:1024
	ds_read_b128 v[152:155], v156 offset:2048
	ds_read_b128 v[156:159], v156 offset:3072
	s_add_i32 s85, s20, 2
	s_cmp_eq_u32 s62, s20
	s_cselect_b32 s24, s14, s77
	s_cselect_b32 s25, s15, s79
	s_cselect_b32 s22, s72, s83
	s_cselect_b32 s23, s71, s84
	s_add_u32 s20, s24, 0x80
	s_addc_u32 s21, s25, 0
	ds_read_b128 v[160:163], v197
	ds_read_b128 v[164:167], v197 offset:1024
	ds_read_b128 v[168:171], v197 offset:2048
	ds_read_b128 v[172:175], v197 offset:3072
	ds_read_b128 v[176:179], v197 offset:4096
	ds_read_b128 v[198:201], v197 offset:5120
	ds_read_b128 v[202:205], v197 offset:6144
	ds_read_b128 v[206:209], v197 offset:7168
	s_add_u32 s86, s77, 0x15ff80
	s_addc_u32 s87, s79, 0
	s_mov_b32 m0, s50
	s_nop 0
	global_load_lds_dwordx4 v182, s[86:87]
	s_nop 0
	s_mov_b32 m0, s52
	s_nop 0
	global_load_lds_dwordx4 v184, s[86:87]
	s_waitcnt vmcnt(8) lgkmcnt(0)
	s_setprio 1
	s_barrier
	v_mfma_f32_16x16x32_bf16 v[124:127], v[128:131], v[160:163], v[124:127]
	v_mfma_f32_16x16x32_bf16 v[120:123], v[136:139], v[160:163], v[120:123]
	v_mfma_f32_16x16x32_bf16 v[108:111], v[128:131], v[168:171], v[108:111]
	v_mfma_f32_16x16x32_bf16 v[104:107], v[136:139], v[168:171], v[104:107]
	v_mfma_f32_16x16x32_bf16 v[92:95], v[128:131], v[176:179], v[92:95]
	v_mfma_f32_16x16x32_bf16 v[88:91], v[136:139], v[176:179], v[88:91]
	v_mfma_f32_16x16x32_bf16 v[76:79], v[128:131], v[202:205], v[76:79]
	v_mfma_f32_16x16x32_bf16 v[72:75], v[136:139], v[202:205], v[72:75]
	v_mfma_f32_16x16x32_bf16 v[124:127], v[132:135], v[164:167], v[124:127]
	v_mfma_f32_16x16x32_bf16 v[120:123], v[140:143], v[164:167], v[120:123]
	v_mfma_f32_16x16x32_bf16 v[108:111], v[132:135], v[172:175], v[108:111]
	v_mfma_f32_16x16x32_bf16 v[104:107], v[140:143], v[172:175], v[104:107]
	v_mfma_f32_16x16x32_bf16 v[92:95], v[132:135], v[198:201], v[92:95]
	v_mfma_f32_16x16x32_bf16 v[88:91], v[140:143], v[198:201], v[88:91]
	v_mfma_f32_16x16x32_bf16 v[76:79], v[132:135], v[206:209], v[76:79]
	v_mfma_f32_16x16x32_bf16 v[72:75], v[140:143], v[206:209], v[72:75]
	v_mfma_f32_16x16x32_bf16 v[116:119], v[144:147], v[160:163], v[116:119]
	v_mfma_f32_16x16x32_bf16 v[112:115], v[152:155], v[160:163], v[112:115]
	v_mfma_f32_16x16x32_bf16 v[100:103], v[144:147], v[168:171], v[100:103]
	v_mfma_f32_16x16x32_bf16 v[96:99], v[152:155], v[168:171], v[96:99]
	v_mfma_f32_16x16x32_bf16 v[84:87], v[144:147], v[176:179], v[84:87]
	v_mfma_f32_16x16x32_bf16 v[80:83], v[152:155], v[176:179], v[80:83]
	v_mfma_f32_16x16x32_bf16 v[68:71], v[144:147], v[202:205], v[68:71]
	v_mfma_f32_16x16x32_bf16 v[64:67], v[152:155], v[202:205], v[64:67]
	v_mfma_f32_16x16x32_bf16 v[116:119], v[148:151], v[164:167], v[116:119]
	v_mfma_f32_16x16x32_bf16 v[112:115], v[156:159], v[164:167], v[112:115]
	v_mfma_f32_16x16x32_bf16 v[100:103], v[148:151], v[172:175], v[100:103]
	v_mfma_f32_16x16x32_bf16 v[96:99], v[156:159], v[172:175], v[96:99]
	v_mfma_f32_16x16x32_bf16 v[84:87], v[148:151], v[198:201], v[84:87]
	v_mfma_f32_16x16x32_bf16 v[80:83], v[156:159], v[198:201], v[80:83]
	v_mfma_f32_16x16x32_bf16 v[68:71], v[148:151], v[206:209], v[68:71]
	v_mfma_f32_16x16x32_bf16 v[64:67], v[156:159], v[206:209], v[64:67]
	s_setprio 0
	s_barrier
	ds_read_b128 v[160:163], v197 offset:16384
	ds_read_b128 v[164:167], v197 offset:17408
	ds_read_b128 v[168:171], v197 offset:18432
	ds_read_b128 v[172:175], v197 offset:19456
	ds_read_b128 v[176:179], v197 offset:20480
	ds_read_b128 v[198:201], v197 offset:21504
	ds_read_b128 v[202:205], v197 offset:22528
	ds_read_b128 v[206:209], v197 offset:23552
	s_mov_b32 m0, s28
	s_nop 0
	global_load_lds_dwordx4 v182, s[24:25]
	s_mov_b32 m0, s34
	s_nop 0
	global_load_lds_dwordx4 v184, s[24:25]
	s_mov_b32 m0, s29
	s_nop 0
	global_load_lds_dwordx4 v183, s[22:23]
	s_add_u32 s86, s22, 0x160000
	s_mov_b32 m0, s30
	s_nop 0
	global_load_lds_dwordx4 v185, s[22:23]
	s_addc_u32 s87, s23, 0
	s_mov_b32 m0, s31
	s_nop 0
	global_load_lds_dwordx4 v183, s[86:87]
	s_nop 0
	s_mov_b32 m0, s33
	s_nop 0
	global_load_lds_dwordx4 v185, s[86:87]
	s_nop 0
	s_nop 0
	s_waitcnt vmcnt(8) lgkmcnt(0)
	s_setprio 1
	s_barrier
	v_mfma_f32_16x16x32_bf16 v[60:63], v[128:131], v[160:163], v[60:63]
	v_mfma_f32_16x16x32_bf16 v[56:59], v[136:139], v[160:163], v[56:59]
	v_mfma_f32_16x16x32_bf16 v[44:47], v[128:131], v[168:171], v[44:47]
	v_mfma_f32_16x16x32_bf16 v[40:43], v[136:139], v[168:171], v[40:43]
	v_mfma_f32_16x16x32_bf16 v[28:31], v[128:131], v[176:179], v[28:31]
	v_mfma_f32_16x16x32_bf16 v[24:27], v[136:139], v[176:179], v[24:27]
	v_mfma_f32_16x16x32_bf16 v[12:15], v[128:131], v[202:205], v[12:15]
	v_mfma_f32_16x16x32_bf16 v[8:11], v[136:139], v[202:205], v[8:11]
	v_mfma_f32_16x16x32_bf16 v[60:63], v[132:135], v[164:167], v[60:63]
	v_mfma_f32_16x16x32_bf16 v[56:59], v[140:143], v[164:167], v[56:59]
	v_mfma_f32_16x16x32_bf16 v[44:47], v[132:135], v[172:175], v[44:47]
	v_mfma_f32_16x16x32_bf16 v[40:43], v[140:143], v[172:175], v[40:43]
	v_mfma_f32_16x16x32_bf16 v[28:31], v[132:135], v[198:201], v[28:31]
	v_mfma_f32_16x16x32_bf16 v[24:27], v[140:143], v[198:201], v[24:27]
	v_mfma_f32_16x16x32_bf16 v[12:15], v[132:135], v[206:209], v[12:15]
	v_mfma_f32_16x16x32_bf16 v[8:11], v[140:143], v[206:209], v[8:11]
	v_mfma_f32_16x16x32_bf16 v[52:55], v[144:147], v[160:163], v[52:55]
	v_mfma_f32_16x16x32_bf16 v[48:51], v[152:155], v[160:163], v[48:51]
	v_mfma_f32_16x16x32_bf16 v[36:39], v[144:147], v[168:171], v[36:39]
	v_mfma_f32_16x16x32_bf16 v[32:35], v[152:155], v[168:171], v[32:35]
	v_mfma_f32_16x16x32_bf16 v[20:23], v[144:147], v[176:179], v[20:23]
	v_mfma_f32_16x16x32_bf16 v[16:19], v[152:155], v[176:179], v[16:19]
	v_mfma_f32_16x16x32_bf16 v[4:7], v[144:147], v[202:205], v[4:7]
	v_mfma_f32_16x16x32_bf16 v[0:3], v[152:155], v[202:205], v[0:3]
	v_mfma_f32_16x16x32_bf16 v[52:55], v[148:151], v[164:167], v[52:55]
	v_mfma_f32_16x16x32_bf16 v[48:51], v[156:159], v[164:167], v[48:51]
	v_mfma_f32_16x16x32_bf16 v[36:39], v[148:151], v[172:175], v[36:39]
	v_mfma_f32_16x16x32_bf16 v[32:35], v[156:159], v[172:175], v[32:35]
	v_mfma_f32_16x16x32_bf16 v[20:23], v[148:151], v[198:201], v[20:23]
	v_mfma_f32_16x16x32_bf16 v[16:19], v[156:159], v[198:201], v[16:19]
	v_mfma_f32_16x16x32_bf16 v[4:7], v[148:151], v[206:209], v[4:7]
	v_mfma_f32_16x16x32_bf16 v[0:3], v[156:159], v[206:209], v[0:3]
	s_setprio 0
	s_barrier
; #define PG8_STAGE(bufoff, gbase, voff) do { _Pragma("unroll") for (int _i = 0; _i < 2; ++_i) \
;         asm volatile("s_mov_b32 m0, %0\n\ts_nop 0\n\tglobal_load_lds_dwordx4 %1, %2" :: "s"(ldsb + (unsigned)((bufoff) + _i * 8192)), "v"((voff)[_i]), "s"(gbase) : "m0", "memory"); } while (0)
; #define PG8_LDA(dst, b, h) do { _Pragma("unroll") for (int m = 0; m < 4; ++m) _Pragma("unroll") for (int k = 0; k < 2; ++k) dst[m][k] = *(const PG8_LAS bf16x8*)(lds + PG8_SA(b, h) + aoff + m * 2048 + k * 1024); } while (0)
; #define PG8_LDB(dst, b, h) do { _Pragma("unroll") for (int n = 0; n < 2; ++n) _Pragma("unroll") for (int k = 0; k < 2; ++k) dst[n][k] = *(const PG8_LAS bf16x8*)(lds + PG8_SB(b, h) + boff + n * 2048 + k * 1024); } while (0)
; #define PG8_MMA(ai, bj, At, Bt) do { __builtin_amdgcn_s_setprio(1); _Pragma("unroll") for (int m = 0; m < 4; ++m) _Pragma("unroll") for (int n = 0; n < 2; ++n) _Pragma("unroll") for (int k = 0; k < 2; ++k) \
;         acc[ai][bj][m][n] = __builtin_amdgcn_mfma_f32_16x16x32_bf16(Bt[n][k], At[m][k], acc[ai][bj][m][n], 0, 0, 0); __builtin_amdgcn_s_setprio(0); } while (0)
; #define PG8_WAIT_V(n) asm volatile("s_waitcnt vmcnt(" #n ")" ::: "memory")
; #define PG8_WAIT_L(n) asm volatile("s_waitcnt lgkmcnt(" #n ")" ::: "memory")
; #define PG8_BAR __builtin_amdgcn_s_barrier()
; #define PG8_SCHED __builtin_amdgcn_sched_barrier(0)
; template <class Epi, class Sched, bool ALIGN_EPI = false, bool SP2 = false>
; __device__ __forceinline__ void gemm_phase(PG8_LAS unsigned char* lds, const Gemm g, const Sched& S, const Epi& E, const int wv) {
;     ...
;             PG8_LDB(B0, 1, 0); PG8_LDB(B1, 1, 1); PG8_SCHED; PG8_LDA(At, 1, 0); PG8_STAGE(PG8_SA(0, 1), a2 + hstepA, voffA);
;             PG8_WAIT_V(8); PG8_WAIT_L(0); PG8_BAR; PG8_MMA(0, 0, At, B0); PG8_MMA(0, 1, At, B1); PG8_BAR; PG8_SCHED;
;             PG8_LDA(At, 1, 1); PG8_STAGE(PG8_SB(1, 0), b3, voffB); PG8_STAGE(PG8_SB(1, 1), b3 + hstepB, voffB); PG8_STAGE(PG8_SA(1, 0), a3, voffA);
;             PG8_WAIT_V(8); PG8_WAIT_L(0); PG8_BAR; PG8_MMA(1, 0, At, B0); PG8_MMA(1, 1, At, B1); PG8_BAR; PG8_SCHED;
	v_add_u32_e32 v140, 0x18000, v196
	v_add_u32_e32 v156, 0x1c000, v196
	ds_read_b128 v[128:131], v140
	ds_read_b128 v[132:135], v140 offset:1024
	ds_read_b128 v[136:139], v140 offset:2048
	ds_read_b128 v[140:143], v140 offset:3072
	ds_read_b128 v[144:147], v156
	ds_read_b128 v[148:151], v156 offset:1024
	ds_read_b128 v[152:155], v156 offset:2048
	ds_read_b128 v[156:159], v156 offset:3072
	ds_read_b128 v[160:163], v197 offset:32768
	ds_read_b128 v[164:167], v197 offset:33792
	ds_read_b128 v[168:171], v197 offset:34816
	ds_read_b128 v[172:175], v197 offset:35840
	ds_read_b128 v[176:179], v197 offset:36864
	ds_read_b128 v[198:201], v197 offset:37888
	ds_read_b128 v[202:205], v197 offset:38912
	ds_read_b128 v[206:209], v197 offset:39936
	s_add_u32 s24, s24, 0x160000
	s_addc_u32 s25, s25, 0
	s_mov_b32 m0, s35
	s_nop 0
	global_load_lds_dwordx4 v182, s[24:25]
	s_nop 0
	s_mov_b32 m0, s36
	s_nop 0
	global_load_lds_dwordx4 v184, s[24:25]
	s_waitcnt vmcnt(8) lgkmcnt(0)
	s_setprio 1
	s_barrier
	v_mfma_f32_16x16x32_bf16 v[124:127], v[128:131], v[160:163], v[124:127]
	v_mfma_f32_16x16x32_bf16 v[120:123], v[136:139], v[160:163], v[120:123]
	v_mfma_f32_16x16x32_bf16 v[108:111], v[128:131], v[168:171], v[108:111]
	v_mfma_f32_16x16x32_bf16 v[104:107], v[136:139], v[168:171], v[104:107]
	v_mfma_f32_16x16x32_bf16 v[92:95], v[128:131], v[176:179], v[92:95]
	v_mfma_f32_16x16x32_bf16 v[88:91], v[136:139], v[176:179], v[88:91]
	v_mfma_f32_16x16x32_bf16 v[76:79], v[128:131], v[202:205], v[76:79]
	v_mfma_f32_16x16x32_bf16 v[72:75], v[136:139], v[202:205], v[72:75]
	v_mfma_f32_16x16x32_bf16 v[124:127], v[132:135], v[164:167], v[124:127]
	v_mfma_f32_16x16x32_bf16 v[120:123], v[140:143], v[164:167], v[120:123]
	v_mfma_f32_16x16x32_bf16 v[108:111], v[132:135], v[172:175], v[108:111]
	v_mfma_f32_16x16x32_bf16 v[104:107], v[140:143], v[172:175], v[104:107]
	v_mfma_f32_16x16x32_bf16 v[92:95], v[132:135], v[198:201], v[92:95]
	v_mfma_f32_16x16x32_bf16 v[88:91], v[140:143], v[198:201], v[88:91]
	v_mfma_f32_16x16x32_bf16 v[76:79], v[132:135], v[206:209], v[76:79]
	v_mfma_f32_16x16x32_bf16 v[72:75], v[140:143], v[206:209], v[72:75]
	v_mfma_f32_16x16x32_bf16 v[116:119], v[144:147], v[160:163], v[116:119]
	v_mfma_f32_16x16x32_bf16 v[112:115], v[152:155], v[160:163], v[112:115]
	v_mfma_f32_16x16x32_bf16 v[100:103], v[144:147], v[168:171], v[100:103]
	v_mfma_f32_16x16x32_bf16 v[96:99], v[152:155], v[168:171], v[96:99]
	v_mfma_f32_16x16x32_bf16 v[84:87], v[144:147], v[176:179], v[84:87]
	v_mfma_f32_16x16x32_bf16 v[80:83], v[152:155], v[176:179], v[80:83]
	v_mfma_f32_16x16x32_bf16 v[68:71], v[144:147], v[202:205], v[68:71]
	v_mfma_f32_16x16x32_bf16 v[64:67], v[152:155], v[202:205], v[64:67]
	v_mfma_f32_16x16x32_bf16 v[116:119], v[148:151], v[164:167], v[116:119]
	v_mfma_f32_16x16x32_bf16 v[112:115], v[156:159], v[164:167], v[112:115]
	v_mfma_f32_16x16x32_bf16 v[100:103], v[148:151], v[172:175], v[100:103]
	v_mfma_f32_16x16x32_bf16 v[96:99], v[156:159], v[172:175], v[96:99]
	v_mfma_f32_16x16x32_bf16 v[84:87], v[148:151], v[198:201], v[84:87]
	v_mfma_f32_16x16x32_bf16 v[80:83], v[156:159], v[198:201], v[80:83]
	v_mfma_f32_16x16x32_bf16 v[68:71], v[148:151], v[206:209], v[68:71]
	v_mfma_f32_16x16x32_bf16 v[64:67], v[156:159], v[206:209], v[64:67]
	s_setprio 0
	s_barrier
	ds_read_b128 v[160:163], v197 offset:49152
	ds_read_b128 v[164:167], v197 offset:50176
	ds_read_b128 v[168:171], v197 offset:51200
	ds_read_b128 v[172:175], v197 offset:52224
	ds_read_b128 v[176:179], v197 offset:53248
	ds_read_b128 v[198:201], v197 offset:54272
	ds_read_b128 v[202:205], v197 offset:55296
	ds_read_b128 v[206:209], v197 offset:56320
	s_add_u32 s24, s22, 0x80
	s_addc_u32 s25, s23, 0
	s_mov_b32 m0, s46
	s_nop 0
	global_load_lds_dwordx4 v182, s[20:21]
	s_mov_b32 m0, s47
	s_nop 0
	global_load_lds_dwordx4 v184, s[20:21]
	s_mov_b32 m0, s44
	s_nop 0
	global_load_lds_dwordx4 v183, s[24:25]
	s_add_u32 s22, s22, 0x160080
	s_mov_b32 m0, s45
	s_nop 0
	global_load_lds_dwordx4 v185, s[24:25]
	s_addc_u32 s23, s23, 0
	s_mov_b32 m0, s48
	s_nop 0
	global_load_lds_dwordx4 v183, s[22:23]
	s_nop 0
	s_mov_b32 m0, s49
	s_nop 0
	global_load_lds_dwordx4 v185, s[22:23]
	s_nop 0
	s_nop 0
	s_waitcnt vmcnt(8) lgkmcnt(0)
	s_setprio 1
	s_barrier
	v_mfma_f32_16x16x32_bf16 v[60:63], v[128:131], v[160:163], v[60:63]
	v_mfma_f32_16x16x32_bf16 v[56:59], v[136:139], v[160:163], v[56:59]
	v_mfma_f32_16x16x32_bf16 v[44:47], v[128:131], v[168:171], v[44:47]
	v_mfma_f32_16x16x32_bf16 v[40:43], v[136:139], v[168:171], v[40:43]
	v_mfma_f32_16x16x32_bf16 v[28:31], v[128:131], v[176:179], v[28:31]
	v_mfma_f32_16x16x32_bf16 v[24:27], v[136:139], v[176:179], v[24:27]
	v_mfma_f32_16x16x32_bf16 v[12:15], v[128:131], v[202:205], v[12:15]
	v_mfma_f32_16x16x32_bf16 v[8:11], v[136:139], v[202:205], v[8:11]
	v_mfma_f32_16x16x32_bf16 v[60:63], v[132:135], v[164:167], v[60:63]
	v_mfma_f32_16x16x32_bf16 v[56:59], v[140:143], v[164:167], v[56:59]
	v_mfma_f32_16x16x32_bf16 v[44:47], v[132:135], v[172:175], v[44:47]
	v_mfma_f32_16x16x32_bf16 v[40:43], v[140:143], v[172:175], v[40:43]
	v_mfma_f32_16x16x32_bf16 v[28:31], v[132:135], v[198:201], v[28:31]
	v_mfma_f32_16x16x32_bf16 v[24:27], v[140:143], v[198:201], v[24:27]
	v_mfma_f32_16x16x32_bf16 v[12:15], v[132:135], v[206:209], v[12:15]
	v_mfma_f32_16x16x32_bf16 v[8:11], v[140:143], v[206:209], v[8:11]
	v_mfma_f32_16x16x32_bf16 v[52:55], v[144:147], v[160:163], v[52:55]
	v_mfma_f32_16x16x32_bf16 v[48:51], v[152:155], v[160:163], v[48:51]
	v_mfma_f32_16x16x32_bf16 v[36:39], v[144:147], v[168:171], v[36:39]
	v_mfma_f32_16x16x32_bf16 v[32:35], v[152:155], v[168:171], v[32:35]
	v_mfma_f32_16x16x32_bf16 v[20:23], v[144:147], v[176:179], v[20:23]
	v_mfma_f32_16x16x32_bf16 v[16:19], v[152:155], v[176:179], v[16:19]
	v_mfma_f32_16x16x32_bf16 v[4:7], v[144:147], v[202:205], v[4:7]
	v_mfma_f32_16x16x32_bf16 v[0:3], v[152:155], v[202:205], v[0:3]
	v_mfma_f32_16x16x32_bf16 v[52:55], v[148:151], v[164:167], v[52:55]
	v_mfma_f32_16x16x32_bf16 v[48:51], v[156:159], v[164:167], v[48:51]
	v_mfma_f32_16x16x32_bf16 v[36:39], v[148:151], v[172:175], v[36:39]
	v_mfma_f32_16x16x32_bf16 v[32:35], v[156:159], v[172:175], v[32:35]
	v_mfma_f32_16x16x32_bf16 v[20:23], v[148:151], v[198:201], v[20:23]
	v_mfma_f32_16x16x32_bf16 v[16:19], v[156:159], v[198:201], v[16:19]
	v_mfma_f32_16x16x32_bf16 v[4:7], v[148:151], v[206:209], v[4:7]
	v_mfma_f32_16x16x32_bf16 v[0:3], v[156:159], v[206:209], v[0:3]
	s_setprio 0
	s_barrier
	s_add_u32 s77, s77, 0x100
	s_addc_u32 s79, s79, 0
	s_add_u32 s83, s83, 0x100
	s_addc_u32 s84, s84, 0
	s_cmp_ge_i32 s85, s65
	s_mov_b32 s20, s85
	s_cbranch_scc0 .LBB0_1244
	s_mov_b32 s79, 0xc00000
	s_and_b64 vcc, exec, s[12:13]
	s_cbranch_vccz .LBB0_1247

; #define PG8_STAGE(bufoff, gbase, voff) do { _Pragma("unroll") for (int _i = 0; _i < 2; ++_i) \
;         asm volatile("s_mov_b32 m0, %0\n\ts_nop 0\n\tglobal_load_lds_dwordx4 %1, %2" :: "s"(ldsb + (unsigned)((bufoff) + _i * 8192)), "v"((voff)[_i]), "s"(gbase) : "m0", "memory"); } while (0)
; #define PG8_LDA(dst, b, h) do { _Pragma("unroll") for (int m = 0; m < 4; ++m) _Pragma("unroll") for (int k = 0; k < 2; ++k) dst[m][k] = *(const PG8_LAS bf16x8*)(lds + PG8_SA(b, h) + aoff + m * 2048 + k * 1024); } while (0)
; #define PG8_LDB(dst, b, h) do { _Pragma("unroll") for (int n = 0; n < 2; ++n) _Pragma("unroll") for (int k = 0; k < 2; ++k) dst[n][k] = *(const PG8_LAS bf16x8*)(lds + PG8_SB(b, h) + boff + n * 2048 + k * 1024); } while (0)
; #define PG8_MMA(ai, bj, At, Bt) do { __builtin_amdgcn_s_setprio(1); _Pragma("unroll") for (int m = 0; m < 4; ++m) _Pragma("unroll") for (int n = 0; n < 2; ++n) _Pragma("unroll") for (int k = 0; k < 2; ++k) \
;         acc[ai][bj][m][n] = __builtin_amdgcn_mfma_f32_16x16x32_bf16(Bt[n][k], At[m][k], acc[ai][bj][m][n], 0, 0, 0); __builtin_amdgcn_s_setprio(0); } while (0)
; #define PG8_WAIT_V(n) asm volatile("s_waitcnt vmcnt(" #n ")" ::: "memory")
; #define PG8_WAIT_L(n) asm volatile("s_waitcnt lgkmcnt(" #n ")" ::: "memory")
; #define PG8_BAR __builtin_amdgcn_s_barrier()
; #define PG8_SCHED __builtin_amdgcn_sched_barrier(0)
; template <class Epi, class Sched, bool ALIGN_EPI = false, bool SP2 = false>
; __device__ __forceinline__ void gemm_phase(PG8_LAS unsigned char* lds, const Gemm g, const Sched& S, const Epi& E, const int wv) {
;     ...
;             PG8_LDB(B0, 0, 0); PG8_LDB(B1, 0, 1); PG8_SCHED; PG8_LDA(At, 0, 0); PG8_STAGE(PG8_SA(1, 1), a1 + hstepA, voffA);
;             PG8_WAIT_V(8); PG8_WAIT_L(0); PG8_BAR; PG8_MMA(0, 0, At, B0); PG8_MMA(0, 1, At, B1); PG8_BAR; PG8_SCHED;
;             PG8_LDA(At, 0, 1); PG8_STAGE(PG8_SB(0, 0), b2, voffB); PG8_STAGE(PG8_SB(0, 1), b2 + hstepB, voffB); PG8_STAGE(PG8_SA(0, 0), a2, voffA);
;             PG8_WAIT_V(8); PG8_WAIT_L(0); PG8_BAR; PG8_MMA(1, 0, At, B0); PG8_MMA(1, 1, At, B1); PG8_BAR; PG8_SCHED;
.LBB0_1336:
	v_add_u32_e32 v140, 0x10000, v220
	v_add_u32_e32 v159, 0x14000, v220
	ds_read_b128 v[128:131], v140
	ds_read_b128 v[132:135], v140 offset:1024
	ds_read_b128 v[136:139], v140 offset:2048
	ds_read_b128 v[140:143], v140 offset:3072
	ds_read_b128 v[144:147], v159
	ds_read_b128 v[148:151], v159 offset:1024
	ds_read_b128 v[152:155], v159 offset:2048
	ds_read_b128 v[160:163], v159 offset:3072
	s_add_i32 vcc_hi, s34, 2
	s_cmp_eq_u32 s25, s34
	s_cselect_b32 s42, s26, s85
	s_cselect_b32 s43, s27, vcc_lo
	s_cselect_b32 s36, s28, s79
	s_cselect_b32 s37, s29, s62
	s_add_u32 s34, s42, 0x80
	s_addc_u32 s35, s43, 0
	ds_read_b128 v[164:167], v221
	ds_read_b128 v[168:171], v221 offset:1024
	ds_read_b128 v[172:175], v221 offset:2048
	ds_read_b128 v[176:179], v221 offset:3072
	ds_read_b128 v[180:183], v221 offset:4096
	ds_read_b128 v[184:187], v221 offset:5120
	ds_read_b128 v[188:191], v221 offset:6144
	ds_read_b128 v[194:197], v221 offset:7168
	s_mov_b32 m0, s71
	s_nop 0
	global_load_lds_dwordx4 v208, s[30:31]
	s_nop 0
	s_mov_b32 m0, s88
	s_nop 0
	global_load_lds_dwordx4 v210, s[30:31]
	s_waitcnt vmcnt(8) lgkmcnt(0)
	s_setprio 1
	s_barrier
	v_mfma_f32_16x16x32_bf16 v[124:127], v[128:131], v[164:167], v[124:127]
	v_mfma_f32_16x16x32_bf16 v[120:123], v[136:139], v[164:167], v[120:123]
	v_mfma_f32_16x16x32_bf16 v[108:111], v[128:131], v[172:175], v[108:111]
	v_mfma_f32_16x16x32_bf16 v[104:107], v[136:139], v[172:175], v[104:107]
	v_mfma_f32_16x16x32_bf16 v[92:95], v[128:131], v[180:183], v[92:95]
	v_mfma_f32_16x16x32_bf16 v[88:91], v[136:139], v[180:183], v[88:91]
	v_mfma_f32_16x16x32_bf16 v[76:79], v[128:131], v[188:191], v[76:79]
	v_mfma_f32_16x16x32_bf16 v[72:75], v[136:139], v[188:191], v[72:75]
	v_mfma_f32_16x16x32_bf16 v[124:127], v[132:135], v[168:171], v[124:127]
	v_mfma_f32_16x16x32_bf16 v[120:123], v[140:143], v[168:171], v[120:123]
	v_mfma_f32_16x16x32_bf16 v[108:111], v[132:135], v[176:179], v[108:111]
	v_mfma_f32_16x16x32_bf16 v[104:107], v[140:143], v[176:179], v[104:107]
	v_mfma_f32_16x16x32_bf16 v[92:95], v[132:135], v[184:187], v[92:95]
	v_mfma_f32_16x16x32_bf16 v[88:91], v[140:143], v[184:187], v[88:91]
	v_mfma_f32_16x16x32_bf16 v[76:79], v[132:135], v[194:197], v[76:79]
	v_mfma_f32_16x16x32_bf16 v[72:75], v[140:143], v[194:197], v[72:75]
	v_mfma_f32_16x16x32_bf16 v[116:119], v[144:147], v[164:167], v[116:119]
	v_mfma_f32_16x16x32_bf16 v[112:115], v[152:155], v[164:167], v[112:115]
	v_mfma_f32_16x16x32_bf16 v[100:103], v[144:147], v[172:175], v[100:103]
	v_mfma_f32_16x16x32_bf16 v[96:99], v[152:155], v[172:175], v[96:99]
	v_mfma_f32_16x16x32_bf16 v[84:87], v[144:147], v[180:183], v[84:87]
	v_mfma_f32_16x16x32_bf16 v[80:83], v[152:155], v[180:183], v[80:83]
	v_mfma_f32_16x16x32_bf16 v[68:71], v[144:147], v[188:191], v[68:71]
	v_mfma_f32_16x16x32_bf16 v[64:67], v[152:155], v[188:191], v[64:67]
	v_mfma_f32_16x16x32_bf16 v[116:119], v[148:151], v[168:171], v[116:119]
	v_mfma_f32_16x16x32_bf16 v[112:115], v[160:163], v[168:171], v[112:115]
	v_mfma_f32_16x16x32_bf16 v[100:103], v[148:151], v[176:179], v[100:103]
	v_mfma_f32_16x16x32_bf16 v[96:99], v[160:163], v[176:179], v[96:99]
	v_mfma_f32_16x16x32_bf16 v[84:87], v[148:151], v[184:187], v[84:87]
	v_mfma_f32_16x16x32_bf16 v[80:83], v[160:163], v[184:187], v[80:83]
	v_mfma_f32_16x16x32_bf16 v[68:71], v[148:151], v[194:197], v[68:71]
	v_mfma_f32_16x16x32_bf16 v[64:67], v[160:163], v[194:197], v[64:67]
	s_setprio 0
	s_barrier
	ds_read_b128 v[164:167], v221 offset:16384
	ds_read_b128 v[168:171], v221 offset:17408
	ds_read_b128 v[172:175], v221 offset:18432
	ds_read_b128 v[176:179], v221 offset:19456
	ds_read_b128 v[180:183], v221 offset:20480
	ds_read_b128 v[184:187], v221 offset:21504
	ds_read_b128 v[188:191], v221 offset:22528
	ds_read_b128 v[194:197], v221 offset:23552
	s_mov_b32 m0, s46
	s_nop 0
	global_load_lds_dwordx4 v208, s[42:43]
	s_mov_b32 m0, s51
	s_nop 0
	global_load_lds_dwordx4 v210, s[42:43]
	s_mov_b32 m0, s47
	s_nop 0
	global_load_lds_dwordx4 v209, s[36:37]
	s_add_u32 s10, s36, 0x160000
	s_mov_b32 m0, s48
	s_nop 0
	global_load_lds_dwordx4 v211, s[36:37]
	s_addc_u32 s11, s37, 0
	s_mov_b32 m0, s49
	s_nop 0
	global_load_lds_dwordx4 v209, s[10:11]
	s_nop 0
	s_mov_b32 m0, s50
	s_nop 0
	global_load_lds_dwordx4 v211, s[10:11]
	s_nop 0
	s_nop 0
	s_waitcnt vmcnt(8) lgkmcnt(0)
	s_setprio 1
	s_barrier
	v_mfma_f32_16x16x32_bf16 v[60:63], v[128:131], v[164:167], v[60:63]
	v_mfma_f32_16x16x32_bf16 v[56:59], v[136:139], v[164:167], v[56:59]
	v_mfma_f32_16x16x32_bf16 v[44:47], v[128:131], v[172:175], v[44:47]
	v_mfma_f32_16x16x32_bf16 v[40:43], v[136:139], v[172:175], v[40:43]
	v_mfma_f32_16x16x32_bf16 v[28:31], v[128:131], v[180:183], v[28:31]
	v_mfma_f32_16x16x32_bf16 v[24:27], v[136:139], v[180:183], v[24:27]
	v_mfma_f32_16x16x32_bf16 v[12:15], v[128:131], v[188:191], v[12:15]
	v_mfma_f32_16x16x32_bf16 v[8:11], v[136:139], v[188:191], v[8:11]
	v_mfma_f32_16x16x32_bf16 v[60:63], v[132:135], v[168:171], v[60:63]
	v_mfma_f32_16x16x32_bf16 v[56:59], v[140:143], v[168:171], v[56:59]
	v_mfma_f32_16x16x32_bf16 v[44:47], v[132:135], v[176:179], v[44:47]
	v_mfma_f32_16x16x32_bf16 v[40:43], v[140:143], v[176:179], v[40:43]
	v_mfma_f32_16x16x32_bf16 v[28:31], v[132:135], v[184:187], v[28:31]
	v_mfma_f32_16x16x32_bf16 v[24:27], v[140:143], v[184:187], v[24:27]
	v_mfma_f32_16x16x32_bf16 v[12:15], v[132:135], v[194:197], v[12:15]
	v_mfma_f32_16x16x32_bf16 v[8:11], v[140:143], v[194:197], v[8:11]
	v_mfma_f32_16x16x32_bf16 v[52:55], v[144:147], v[164:167], v[52:55]
	v_mfma_f32_16x16x32_bf16 v[48:51], v[152:155], v[164:167], v[48:51]
	v_mfma_f32_16x16x32_bf16 v[36:39], v[144:147], v[172:175], v[36:39]
	v_mfma_f32_16x16x32_bf16 v[32:35], v[152:155], v[172:175], v[32:35]
	v_mfma_f32_16x16x32_bf16 v[20:23], v[144:147], v[180:183], v[20:23]
	v_mfma_f32_16x16x32_bf16 v[16:19], v[152:155], v[180:183], v[16:19]
	v_mfma_f32_16x16x32_bf16 v[4:7], v[144:147], v[188:191], v[4:7]
	v_mfma_f32_16x16x32_bf16 v[0:3], v[152:155], v[188:191], v[0:3]
	v_mfma_f32_16x16x32_bf16 v[52:55], v[148:151], v[168:171], v[52:55]
	v_mfma_f32_16x16x32_bf16 v[48:51], v[160:163], v[168:171], v[48:51]
	v_mfma_f32_16x16x32_bf16 v[36:39], v[148:151], v[176:179], v[36:39]
	v_mfma_f32_16x16x32_bf16 v[32:35], v[160:163], v[176:179], v[32:35]
	v_mfma_f32_16x16x32_bf16 v[20:23], v[148:151], v[184:187], v[20:23]
	v_mfma_f32_16x16x32_bf16 v[16:19], v[160:163], v[184:187], v[16:19]
	v_mfma_f32_16x16x32_bf16 v[4:7], v[148:151], v[194:197], v[4:7]
	v_mfma_f32_16x16x32_bf16 v[0:3], v[160:163], v[194:197], v[0:3]
	s_setprio 0
	s_barrier
; #define PG8_STAGE(bufoff, gbase, voff) do { _Pragma("unroll") for (int _i = 0; _i < 2; ++_i) \
;         asm volatile("s_mov_b32 m0, %0\n\ts_nop 0\n\tglobal_load_lds_dwordx4 %1, %2" :: "s"(ldsb + (unsigned)((bufoff) + _i * 8192)), "v"((voff)[_i]), "s"(gbase) : "m0", "memory"); } while (0)
; #define PG8_LDA(dst, b, h) do { _Pragma("unroll") for (int m = 0; m < 4; ++m) _Pragma("unroll") for (int k = 0; k < 2; ++k) dst[m][k] = *(const PG8_LAS bf16x8*)(lds + PG8_SA(b, h) + aoff + m * 2048 + k * 1024); } while (0)
; #define PG8_LDB(dst, b, h) do { _Pragma("unroll") for (int n = 0; n < 2; ++n) _Pragma("unroll") for (int k = 0; k < 2; ++k) dst[n][k] = *(const PG8_LAS bf16x8*)(lds + PG8_SB(b, h) + boff + n * 2048 + k * 1024); } while (0)
; #define PG8_MMA(ai, bj, At, Bt) do { __builtin_amdgcn_s_setprio(1); _Pragma("unroll") for (int m = 0; m < 4; ++m) _Pragma("unroll") for (int n = 0; n < 2; ++n) _Pragma("unroll") for (int k = 0; k < 2; ++k) \
;         acc[ai][bj][m][n] = __builtin_amdgcn_mfma_f32_16x16x32_bf16(Bt[n][k], At[m][k], acc[ai][bj][m][n], 0, 0, 0); __builtin_amdgcn_s_setprio(0); } while (0)
; #define PG8_WAIT_V(n) asm volatile("s_waitcnt vmcnt(" #n ")" ::: "memory")
; #define PG8_WAIT_L(n) asm volatile("s_waitcnt lgkmcnt(" #n ")" ::: "memory")
; #define PG8_BAR __builtin_amdgcn_s_barrier()
; #define PG8_SCHED __builtin_amdgcn_sched_barrier(0)
; template <class Epi, class Sched, bool ALIGN_EPI = false, bool SP2 = false>
; __device__ __forceinline__ void gemm_phase(PG8_LAS unsigned char* lds, const Gemm g, const Sched& S, const Epi& E, const int wv) {
;     ...
;             PG8_LDB(B0, 1, 0); PG8_LDB(B1, 1, 1); PG8_SCHED; PG8_LDA(At, 1, 0); PG8_STAGE(PG8_SA(0, 1), a2 + hstepA, voffA);
;             PG8_WAIT_V(8); PG8_WAIT_L(0); PG8_BAR; PG8_MMA(0, 0, At, B0); PG8_MMA(0, 1, At, B1); PG8_BAR; PG8_SCHED;
;             PG8_LDA(At, 1, 1); PG8_STAGE(PG8_SB(1, 0), b3, voffB); PG8_STAGE(PG8_SB(1, 1), b3 + hstepB, voffB); PG8_STAGE(PG8_SA(1, 0), a3, voffA);
;             PG8_WAIT_V(8); PG8_WAIT_L(0); PG8_BAR; PG8_MMA(1, 0, At, B0); PG8_MMA(1, 1, At, B1); PG8_BAR; PG8_SCHED;
	v_add_u32_e32 v140, 0x18000, v220
	v_add_u32_e32 v159, 0x1c000, v220
	ds_read_b128 v[128:131], v140
	ds_read_b128 v[132:135], v140 offset:1024
	ds_read_b128 v[136:139], v140 offset:2048
	ds_read_b128 v[140:143], v140 offset:3072
	ds_read_b128 v[144:147], v159
	ds_read_b128 v[148:151], v159 offset:1024
	ds_read_b128 v[152:155], v159 offset:2048
	ds_read_b128 v[160:163], v159 offset:3072
	ds_read_b128 v[164:167], v221 offset:32768
	ds_read_b128 v[168:171], v221 offset:33792
	ds_read_b128 v[172:175], v221 offset:34816
	ds_read_b128 v[176:179], v221 offset:35840
	ds_read_b128 v[180:183], v221 offset:36864
	ds_read_b128 v[184:187], v221 offset:37888
	ds_read_b128 v[188:191], v221 offset:38912
	ds_read_b128 v[194:197], v221 offset:39936
	s_add_u32 s10, s42, 0x160000
	s_addc_u32 s11, s43, 0
	s_mov_b32 m0, s52
	s_nop 0
	global_load_lds_dwordx4 v208, s[10:11]
	s_nop 0
	s_mov_b32 m0, s53
	s_nop 0
	global_load_lds_dwordx4 v210, s[10:11]
	s_waitcnt vmcnt(8) lgkmcnt(0)
	s_setprio 1
	s_barrier
	v_mfma_f32_16x16x32_bf16 v[124:127], v[128:131], v[164:167], v[124:127]
	v_mfma_f32_16x16x32_bf16 v[120:123], v[136:139], v[164:167], v[120:123]
	v_mfma_f32_16x16x32_bf16 v[108:111], v[128:131], v[172:175], v[108:111]
	v_mfma_f32_16x16x32_bf16 v[104:107], v[136:139], v[172:175], v[104:107]
	v_mfma_f32_16x16x32_bf16 v[92:95], v[128:131], v[180:183], v[92:95]
	v_mfma_f32_16x16x32_bf16 v[88:91], v[136:139], v[180:183], v[88:91]
	v_mfma_f32_16x16x32_bf16 v[76:79], v[128:131], v[188:191], v[76:79]
	v_mfma_f32_16x16x32_bf16 v[72:75], v[136:139], v[188:191], v[72:75]
	v_mfma_f32_16x16x32_bf16 v[124:127], v[132:135], v[168:171], v[124:127]
	v_mfma_f32_16x16x32_bf16 v[120:123], v[140:143], v[168:171], v[120:123]
	v_mfma_f32_16x16x32_bf16 v[108:111], v[132:135], v[176:179], v[108:111]
	v_mfma_f32_16x16x32_bf16 v[104:107], v[140:143], v[176:179], v[104:107]
	v_mfma_f32_16x16x32_bf16 v[92:95], v[132:135], v[184:187], v[92:95]
	v_mfma_f32_16x16x32_bf16 v[88:91], v[140:143], v[184:187], v[88:91]
	v_mfma_f32_16x16x32_bf16 v[76:79], v[132:135], v[194:197], v[76:79]
	v_mfma_f32_16x16x32_bf16 v[72:75], v[140:143], v[194:197], v[72:75]
	v_mfma_f32_16x16x32_bf16 v[116:119], v[144:147], v[164:167], v[116:119]
	v_mfma_f32_16x16x32_bf16 v[112:115], v[152:155], v[164:167], v[112:115]
	v_mfma_f32_16x16x32_bf16 v[100:103], v[144:147], v[172:175], v[100:103]
	v_mfma_f32_16x16x32_bf16 v[96:99], v[152:155], v[172:175], v[96:99]
	v_mfma_f32_16x16x32_bf16 v[84:87], v[144:147], v[180:183], v[84:87]
	v_mfma_f32_16x16x32_bf16 v[80:83], v[152:155], v[180:183], v[80:83]
	v_mfma_f32_16x16x32_bf16 v[68:71], v[144:147], v[188:191], v[68:71]
	v_mfma_f32_16x16x32_bf16 v[64:67], v[152:155], v[188:191], v[64:67]
	v_mfma_f32_16x16x32_bf16 v[116:119], v[148:151], v[168:171], v[116:119]
	v_mfma_f32_16x16x32_bf16 v[112:115], v[160:163], v[168:171], v[112:115]
	v_mfma_f32_16x16x32_bf16 v[100:103], v[148:151], v[176:179], v[100:103]
	v_mfma_f32_16x16x32_bf16 v[96:99], v[160:163], v[176:179], v[96:99]
	v_mfma_f32_16x16x32_bf16 v[84:87], v[148:151], v[184:187], v[84:87]
	v_mfma_f32_16x16x32_bf16 v[80:83], v[160:163], v[184:187], v[80:83]
	v_mfma_f32_16x16x32_bf16 v[68:71], v[148:151], v[194:197], v[68:71]
	v_mfma_f32_16x16x32_bf16 v[64:67], v[160:163], v[194:197], v[64:67]
	s_setprio 0
	s_barrier
	ds_read_b128 v[164:167], v221 offset:49152
	ds_read_b128 v[168:171], v221 offset:50176
	ds_read_b128 v[172:175], v221 offset:51200
	ds_read_b128 v[176:179], v221 offset:52224
	ds_read_b128 v[180:183], v221 offset:53248
	ds_read_b128 v[184:187], v221 offset:54272
	ds_read_b128 v[188:191], v221 offset:55296
	ds_read_b128 v[194:197], v221 offset:56320
	s_add_u32 s10, s36, 0x80
	s_addc_u32 s11, s37, 0
	s_mov_b32 m0, s60
	s_nop 0
	global_load_lds_dwordx4 v208, s[34:35]
	s_mov_b32 m0, s89
	s_nop 0
	global_load_lds_dwordx4 v210, s[34:35]
	s_mov_b32 m0, s87
	s_nop 0
	global_load_lds_dwordx4 v209, s[10:11]
	s_nop 0
	s_mov_b32 m0, s83
	s_nop 0
	global_load_lds_dwordx4 v211, s[10:11]
	s_add_u32 s10, s36, 0x160080
	s_addc_u32 s11, s37, 0
	s_mov_b32 m0, s92
	s_nop 0
	global_load_lds_dwordx4 v209, s[10:11]
	s_nop 0
	s_mov_b32 m0, s93
	s_nop 0
	global_load_lds_dwordx4 v211, s[10:11]
	s_nop 0
	s_nop 0
	s_waitcnt vmcnt(8) lgkmcnt(0)
	s_setprio 1
	s_barrier
	v_mfma_f32_16x16x32_bf16 v[60:63], v[128:131], v[164:167], v[60:63]
	v_mfma_f32_16x16x32_bf16 v[56:59], v[136:139], v[164:167], v[56:59]
	v_mfma_f32_16x16x32_bf16 v[44:47], v[128:131], v[172:175], v[44:47]
	v_mfma_f32_16x16x32_bf16 v[40:43], v[136:139], v[172:175], v[40:43]
	v_mfma_f32_16x16x32_bf16 v[28:31], v[128:131], v[180:183], v[28:31]
	v_mfma_f32_16x16x32_bf16 v[24:27], v[136:139], v[180:183], v[24:27]
	v_mfma_f32_16x16x32_bf16 v[12:15], v[128:131], v[188:191], v[12:15]
	v_mfma_f32_16x16x32_bf16 v[8:11], v[136:139], v[188:191], v[8:11]
	v_mfma_f32_16x16x32_bf16 v[60:63], v[132:135], v[168:171], v[60:63]
	v_mfma_f32_16x16x32_bf16 v[56:59], v[140:143], v[168:171], v[56:59]
	v_mfma_f32_16x16x32_bf16 v[44:47], v[132:135], v[176:179], v[44:47]
	v_mfma_f32_16x16x32_bf16 v[40:43], v[140:143], v[176:179], v[40:43]
	v_mfma_f32_16x16x32_bf16 v[28:31], v[132:135], v[184:187], v[28:31]
	v_mfma_f32_16x16x32_bf16 v[24:27], v[140:143], v[184:187], v[24:27]
	v_mfma_f32_16x16x32_bf16 v[12:15], v[132:135], v[194:197], v[12:15]
	v_mfma_f32_16x16x32_bf16 v[8:11], v[140:143], v[194:197], v[8:11]
	v_mfma_f32_16x16x32_bf16 v[52:55], v[144:147], v[164:167], v[52:55]
	v_mfma_f32_16x16x32_bf16 v[48:51], v[152:155], v[164:167], v[48:51]
	v_mfma_f32_16x16x32_bf16 v[36:39], v[144:147], v[172:175], v[36:39]
	v_mfma_f32_16x16x32_bf16 v[32:35], v[152:155], v[172:175], v[32:35]
	v_mfma_f32_16x16x32_bf16 v[20:23], v[144:147], v[180:183], v[20:23]
	v_mfma_f32_16x16x32_bf16 v[16:19], v[152:155], v[180:183], v[16:19]
	v_mfma_f32_16x16x32_bf16 v[4:7], v[144:147], v[188:191], v[4:7]
	v_mfma_f32_16x16x32_bf16 v[0:3], v[152:155], v[188:191], v[0:3]
	v_mfma_f32_16x16x32_bf16 v[52:55], v[148:151], v[168:171], v[52:55]
	v_mfma_f32_16x16x32_bf16 v[48:51], v[160:163], v[168:171], v[48:51]
	v_mfma_f32_16x16x32_bf16 v[36:39], v[148:151], v[176:179], v[36:39]
	v_mfma_f32_16x16x32_bf16 v[32:35], v[160:163], v[176:179], v[32:35]
	v_mfma_f32_16x16x32_bf16 v[20:23], v[148:151], v[184:187], v[20:23]
	v_mfma_f32_16x16x32_bf16 v[16:19], v[160:163], v[184:187], v[16:19]
	v_mfma_f32_16x16x32_bf16 v[4:7], v[148:151], v[194:197], v[4:7]
	v_mfma_f32_16x16x32_bf16 v[0:3], v[160:163], v[194:197], v[0:3]
	s_setprio 0
	s_barrier
	s_add_u32 s85, s85, 0x100
	s_addc_u32 vcc_lo, vcc_lo, 0
	s_add_u32 s79, s79, 0x100
	s_addc_u32 s62, s62, 0
	s_add_u32 s30, s30, 0x100
	s_addc_u32 s31, s31, 0
	s_cmp_ge_i32 vcc_hi, s40
	s_mov_b32 s34, vcc_hi
	s_cbranch_scc0 .LBB0_1336
	s_mov_b32 s79, 0xc00000
	s_and_b64 vcc, exec, s[20:21]
	s_cbranch_vccz .LBB0_1339
